# xor-16/xor-32 wave reductions (attention row max, attention and out-projection sums of squares) with v_permlane16/32_swap instead of ds_bpermute round trips
# speedup vs baseline: 1.0040x; 1.0017x over previous
.LBB0_1070:
	v_max_f32_e32 v81, v137, v137
	v_mov_b32_e32 v80, v81
	s_nop 1
	v_permlane16_swap_b32_e32 v80, v81
	v_max_f32_e32 v80, v80, v81
	v_mov_b32_e32 v81, v80
	s_nop 1
	v_permlane32_swap_b32_e32 v80, v81
	v_max3_f32 v88, v136, v80, v81
	v_sub_f32_e32 v80, v136, v88
	v_exp_f32_e32 v90, v80
	v_sub_f32_e32 v80, v120, v88
	v_exp_f32_e32 v80, v80
	v_sub_f32_e32 v82, v121, v88
	v_exp_f32_e32 v82, v82
	v_sub_f32_e32 v83, v112, v88
	v_exp_f32_e32 v83, v83
	v_sub_f32_e32 v84, v113, v88
	v_exp_f32_e32 v84, v84
	v_sub_f32_e32 v85, v108, v88
	v_fma_f32 v81, v135, v90, v80
	v_exp_f32_e32 v85, v85
	v_sub_f32_e32 v86, v109, v88
	v_add_f32_e32 v81, v82, v81
	v_exp_f32_e32 v86, v86
	v_sub_f32_e32 v87, v106, v88
	v_add_f32_e32 v81, v83, v81
	v_exp_f32_e32 v87, v87
	v_sub_f32_e32 v89, v107, v88
	v_add_f32_e32 v81, v84, v81
	v_exp_f32_e32 v89, v89
	v_add_f32_e32 v81, v85, v81
	v_add_f32_e32 v81, v86, v81
	v_add_f32_e32 v81, v87, v81
	v_add_f32_e32 v91, v89, v81
	v_cvt_pk_bf16_f32 v81, v83, v84
	v_sub_f32_e32 v84, v110, v88
	v_cvt_pk_bf16_f32 v83, v87, v89
	v_exp_f32_e32 v89, v84
	v_sub_f32_e32 v84, v111, v88
	v_exp_f32_e32 v92, v84
	v_sub_f32_e32 v84, v114, v88
	v_exp_f32_e32 v93, v84
	v_sub_f32_e32 v84, v115, v88
	v_exp_f32_e32 v94, v84
	v_sub_f32_e32 v84, v116, v88
	v_exp_f32_e32 v95, v84
	v_sub_f32_e32 v84, v117, v88
	v_exp_f32_e32 v106, v84
	v_sub_f32_e32 v84, v118, v88
	v_exp_f32_e32 v107, v84
	v_sub_f32_e32 v84, v119, v88
	v_exp_f32_e32 v135, v84
	v_cvt_pk_bf16_f32 v84, v89, v92
	v_add_f32_e32 v89, v89, v91
	v_add_f32_e32 v89, v92, v89
	v_add_f32_e32 v89, v93, v89
	v_add_f32_e32 v89, v94, v89
	v_add_f32_e32 v89, v95, v89
	v_cvt_pk_bf16_f32 v80, v80, v82
	v_cvt_pk_bf16_f32 v82, v85, v86
	v_cvt_pk_bf16_f32 v85, v93, v94
	v_add_f32_e32 v89, v106, v89
	v_cvt_pk_bf16_f32 v86, v95, v106
	v_cvt_pk_bf16_f32 v87, v107, v135
	v_pk_mul_f32 v[74:75], v[74:75], v[90:91] op_sel_hi:[1,0]
	v_pk_mul_f32 v[72:73], v[72:73], v[90:91] op_sel_hi:[1,0]
	v_pk_mul_f32 v[70:71], v[70:71], v[90:91] op_sel_hi:[1,0]
	v_pk_mul_f32 v[68:69], v[68:69], v[90:91] op_sel_hi:[1,0]
	v_pk_mul_f32 v[58:59], v[58:59], v[90:91] op_sel_hi:[1,0]
	v_pk_mul_f32 v[56:57], v[56:57], v[90:91] op_sel_hi:[1,0]
	v_pk_mul_f32 v[18:19], v[18:19], v[90:91] op_sel_hi:[1,0]
	v_pk_mul_f32 v[16:17], v[16:17], v[90:91] op_sel_hi:[1,0]
	v_pk_mul_f32 v[30:31], v[30:31], v[90:91] op_sel_hi:[1,0]
	v_pk_mul_f32 v[28:29], v[28:29], v[90:91] op_sel_hi:[1,0]
	v_pk_mul_f32 v[22:23], v[22:23], v[90:91] op_sel_hi:[1,0]
	v_pk_mul_f32 v[20:21], v[20:21], v[90:91] op_sel_hi:[1,0]
	v_pk_mul_f32 v[26:27], v[26:27], v[90:91] op_sel_hi:[1,0]
	v_pk_mul_f32 v[24:25], v[24:25], v[90:91] op_sel_hi:[1,0]
	v_pk_mul_f32 v[78:79], v[78:79], v[90:91] op_sel_hi:[1,0]
	v_pk_mul_f32 v[76:77], v[76:77], v[90:91] op_sel_hi:[1,0]
	v_add_f32_e32 v89, v107, v89
	ds_read_b128 v[90:93], v134 offset:34816
	ds_read_b128 v[106:109], v134 offset:34880
	ds_read_b128 v[110:113], v134 offset:37120
	ds_read_b128 v[114:117], v134 offset:37184
	ds_read_b128 v[118:121], v134 offset:39424
	ds_read_b128 v[136:139], v134 offset:39488
	ds_read_b128 v[140:143], v134 offset:41728
	ds_read_b128 v[144:147], v134 offset:41792
	s_waitcnt lgkmcnt(7)
	v_mfma_f32_16x16x32_bf16 v[72:75], v[90:93], v[80:83], v[72:75]
	s_waitcnt lgkmcnt(5)
	v_mfma_f32_16x16x32_bf16 v[68:71], v[110:113], v[80:83], v[68:71]
	s_waitcnt lgkmcnt(3)
	v_mfma_f32_16x16x32_bf16 v[56:59], v[118:121], v[80:83], v[56:59]
	s_waitcnt lgkmcnt(1)
	v_mfma_f32_16x16x32_bf16 v[16:19], v[140:143], v[80:83], v[16:19]
	v_mfma_f32_16x16x32_bf16 v[72:75], v[106:109], v[84:87], v[72:75]
	v_mfma_f32_16x16x32_bf16 v[68:71], v[114:117], v[84:87], v[68:71]
	v_mfma_f32_16x16x32_bf16 v[56:59], v[136:139], v[84:87], v[56:59]
	s_waitcnt lgkmcnt(0)
	v_mfma_f32_16x16x32_bf16 v[16:19], v[144:147], v[84:87], v[16:19]
	ds_read_b128 v[90:93], v134 offset:44032
	ds_read_b128 v[106:109], v134 offset:44096
	ds_read_b128 v[110:113], v134 offset:46336
	ds_read_b128 v[114:117], v134 offset:46400
	ds_read_b128 v[118:121], v134 offset:48640
	ds_read_b128 v[136:139], v134 offset:48704
	ds_read_b128 v[140:143], v134 offset:50944
	ds_read_b128 v[144:147], v134 offset:51008
	s_waitcnt lgkmcnt(7)
	v_mfma_f32_16x16x32_bf16 v[28:31], v[90:93], v[80:83], v[28:31]
	s_waitcnt lgkmcnt(5)
	v_mfma_f32_16x16x32_bf16 v[20:23], v[110:113], v[80:83], v[20:23]
	s_waitcnt lgkmcnt(3)
	v_mfma_f32_16x16x32_bf16 v[24:27], v[118:121], v[80:83], v[24:27]
	s_waitcnt lgkmcnt(1)
	v_mfma_f32_16x16x32_bf16 v[76:79], v[140:143], v[80:83], v[76:79]
	v_mfma_f32_16x16x32_bf16 v[28:31], v[106:109], v[84:87], v[28:31]
	v_mfma_f32_16x16x32_bf16 v[20:23], v[114:117], v[84:87], v[20:23]
	v_mfma_f32_16x16x32_bf16 v[24:27], v[136:139], v[84:87], v[24:27]
	s_waitcnt lgkmcnt(0)
	v_mfma_f32_16x16x32_bf16 v[76:79], v[144:147], v[84:87], v[76:79]
	v_add_f32_e32 v135, v135, v89
	s_andn2_b64 vcc, exec, s[76:77]
	s_add_i32 s39, s39, 1
	s_cbranch_vccz .LBB0_1072
	v_mov_b32_e32 v136, v88
	v_add_u32_e32 v131, s32, v131
	v_add_u32_e32 v132, s32, v132
	v_add_u32_e32 v148, s32, v148
	v_add_u32_e32 v133, s32, v133
	v_add_u32_e32 v134, s32, v134
	s_sub_i32 s32, 0, s32
	s_branch .LBB0_1056
.LBB0_1072:
	s_load_dwordx2 s[4:5], s[82:83], 0x40
	v_lshlrev_b32_e32 v0, 1, v208
	v_mov_b32_e32 v1, v209
	v_or_b32_e32 v10, s8, v208
	v_ashrrev_i32_e32 v11, 31, v10
	s_waitcnt lgkmcnt(0)
	s_add_u32 s76, s4, s14
	s_addc_u32 s77, s5, s15
	s_add_i32 s4, s8, 0x1000
	s_ashr_i32 s4, s4, 7
	s_ashr_i32 s5, s4, 31
	s_lshl_b64 s[4:5], s[4:5], 21
	s_add_u32 s4, s56, s4
	s_addc_u32 s5, s57, s5
	v_lshl_add_u64 v[2:3], s[4:5], 0, v[98:99]
	v_lshl_add_u64 v[8:9], v[2:3], 0, v[0:1]
	global_load_dwordx2 v[14:15], v[8:9], off
	v_mov_b32_e32 v2, v135
	s_nop 1
	v_permlane16_swap_b32_e32 v135, v2
	v_lshlrev_b64 v[0:1], 12, v[96:97]
	v_lshl_add_u64 v[0:1], s[50:51], 0, v[0:1]
	v_lshl_add_u64 v[4:5], v[0:1], 0, s[68:69]
	v_lshl_add_u64 v[0:1], v[10:11], 2, s[76:77]
	s_waitcnt lgkmcnt(0)
	v_add_f32_e32 v2, v135, v2
	v_mov_b32_e32 v3, v2
	s_nop 1
	v_permlane32_swap_b32_e32 v2, v3
	s_ashr_i32 s9, s8, 31
	s_mov_b32 s86, s46
	s_waitcnt lgkmcnt(0)
	v_add_f32_e32 v6, v2, v3
	v_div_scale_f32 v7, s[4:5], v6, v6, 1.0
	v_rcp_f32_e32 v12, v7
	v_div_scale_f32 v13, vcc, 1.0, v6, 1.0
	global_load_dwordx2 v[154:155], v[8:9], off offset:32
	global_load_dwordx2 v[156:157], v[8:9], off offset:64
	global_load_dwordx2 v[158:159], v[8:9], off offset:96
	global_load_dwordx2 v[160:161], v[8:9], off offset:128
	global_load_dwordx2 v[162:163], v[8:9], off offset:160
	global_load_dwordx2 v[164:165], v[8:9], off offset:192
	global_load_dwordx2 v[166:167], v[8:9], off offset:224
	global_load_dwordx4 v[168:171], v[0:1], off offset:64
	global_load_dwordx4 v[172:175], v[0:1], off offset:128
	global_load_dwordx4 v[176:179], v[0:1], off offset:192
	global_load_dwordx4 v[180:183], v[0:1], off offset:256
	global_load_dwordx4 v[184:187], v[0:1], off offset:320
	global_load_dwordx4 v[188:191], v[0:1], off offset:384
	global_load_dwordx4 v[192:195], v[0:1], off offset:448
	global_load_dwordx4 v[0:3], v[0:1], off
	s_waitcnt vmcnt(8)
	v_fma_f32 v32, -v7, v12, 1.0
	v_fmac_f32_e32 v12, v32, v12
	v_mul_f32_e32 v32, v13, v12
	v_fma_f32 v33, -v7, v32, v13
	v_fmac_f32_e32 v32, v33, v12
	v_fma_f32 v7, -v7, v32, v13
	v_div_fmas_f32 v7, v7, v12, v32
	s_waitcnt vmcnt(6)
	v_div_fixup_f32 v46, v7, v6, 1.0
	v_pk_mul_f32 v[12:13], v[76:77], v[46:47] op_sel_hi:[1,0]
	v_pk_mul_f32 v[6:7], v[78:79], v[46:47] op_sel_hi:[1,0]
	v_pk_mul_f32 v[40:41], v[74:75], v[46:47] op_sel_hi:[1,0]
	v_pk_mul_f32 v[42:43], v[72:73], v[46:47] op_sel_hi:[1,0]
	v_pk_mul_f32 v[44:45], v[70:71], v[46:47] op_sel_hi:[1,0]
	s_waitcnt vmcnt(5)
	v_pk_mul_f32 v[48:49], v[68:69], v[46:47] op_sel_hi:[1,0]
	v_pk_mul_f32 v[34:35], v[58:59], v[46:47] op_sel_hi:[1,0]
	v_pk_mul_f32 v[38:39], v[56:57], v[46:47] op_sel_hi:[1,0]
	v_pk_mul_f32 v[32:33], v[18:19], v[46:47] op_sel_hi:[1,0]
	v_pk_mul_f32 v[56:57], v[42:43], v[42:43]
	s_waitcnt vmcnt(4)
	v_pk_mul_f32 v[54:55], v[40:41], v[40:41]
	s_waitcnt vmcnt(3)
	v_pk_mul_f32 v[60:61], v[48:49], v[48:49]
	v_pk_mul_f32 v[58:59], v[44:45], v[44:45]
	s_waitcnt vmcnt(2)
	v_pk_mul_f32 v[64:65], v[38:39], v[38:39]
	v_pk_mul_f32 v[62:63], v[34:35], v[34:35]
	v_pk_mul_f32 v[66:67], v[32:33], v[32:33]
	v_pk_mul_f32 v[50:51], v[12:13], v[12:13]
	v_pk_mul_f32 v[52:53], v[6:7], v[6:7]
	s_waitcnt vmcnt(1)
	v_lshlrev_b32_e32 v37, 16, v14
	v_and_b32_e32 v47, 0xffff0000, v14
	v_lshlrev_b32_e32 v80, 16, v15
	v_and_b32_e32 v36, 0xffff0000, v15
	v_mul_f32_e32 v14, 0xbfb8aa3b, v37
	v_mul_f32_e32 v15, 0xbfb8aa3b, v47
	v_mul_f32_e32 v18, 0xbfb8aa3b, v80
	v_mul_f32_e32 v19, 0xbfb8aa3b, v36
	v_exp_f32_e32 v14, v14
	v_exp_f32_e32 v15, v15
	v_exp_f32_e32 v18, v18
	v_exp_f32_e32 v19, v19
	v_pk_add_f32 v[14:15], v[14:15], 1.0 op_sel_hi:[1,0]
	s_nop 0
	v_div_scale_f32 v70, s[4:5], v14, v14, v37
	v_pk_add_f32 v[68:69], v[18:19], 1.0 op_sel_hi:[1,0]
	v_div_scale_f32 v18, s[4:5], v15, v15, v47
	v_rcp_f32_e32 v74, v18
	v_div_scale_f32 v72, s[6:7], v69, v69, v36
	v_rcp_f32_e32 v75, v70
	v_rcp_f32_e32 v76, v72
	v_fma_f32 v77, -v18, v74, 1.0
	v_div_scale_f32 v19, vcc, v47, v15, v47
	v_fma_f32 v78, -v70, v75, 1.0
	v_fmac_f32_e32 v74, v77, v74
	v_div_scale_f32 v71, s[4:5], v37, v14, v37
	v_fma_f32 v79, -v72, v76, 1.0
	v_fmac_f32_e32 v75, v78, v75
	v_mul_f32_e32 v77, v19, v74
	v_div_scale_f32 v73, s[6:7], v36, v69, v36
	v_fmac_f32_e32 v76, v79, v76
	v_mul_f32_e32 v78, v71, v75
	v_fma_f32 v83, -v18, v77, v19
	v_mul_f32_e32 v79, v73, v76
	v_fma_f32 v84, -v70, v78, v71
	v_fmac_f32_e32 v77, v83, v74
	v_fma_f32 v85, -v72, v79, v73
	v_fmac_f32_e32 v78, v84, v75
	v_fma_f32 v18, -v18, v77, v19
	v_fmac_f32_e32 v79, v85, v76
	v_fma_f32 v19, -v70, v78, v71
	v_div_fmas_f32 v18, v18, v74, v77
	s_mov_b64 vcc, s[4:5]
	v_fma_f32 v72, -v72, v79, v73
	v_div_fixup_f32 v71, v18, v15, v47
	v_div_fmas_f32 v15, v19, v75, v78
	s_mov_b64 vcc, s[6:7]
	v_div_fixup_f32 v70, v15, v14, v37
	v_div_fmas_f32 v14, v72, v76, v79
	v_div_fixup_f32 v47, v14, v69, v36
	v_pk_mul_f32 v[36:37], v[16:17], v[46:47] op_sel_hi:[1,0]
	v_pk_mul_f32 v[30:31], v[30:31], v[46:47] op_sel_hi:[1,0]
	v_pk_mul_f32 v[28:29], v[28:29], v[46:47] op_sel_hi:[1,0]
	v_pk_mul_f32 v[22:23], v[22:23], v[46:47] op_sel_hi:[1,0]
	v_pk_mul_f32 v[20:21], v[20:21], v[46:47] op_sel_hi:[1,0]
	v_pk_mul_f32 v[16:17], v[26:27], v[46:47] op_sel_hi:[1,0]
	v_pk_mul_f32 v[18:19], v[24:25], v[46:47] op_sel_hi:[1,0]
	v_add_f32_e32 v46, v56, v57
	v_add_f32_e32 v46, v54, v46
	v_add_f32_e32 v46, v55, v46
	v_add_f32_e32 v46, v60, v46
	v_add_f32_e32 v46, v61, v46
	v_add_f32_e32 v46, v58, v46
	v_add_f32_e32 v46, v59, v46
	v_add_f32_e32 v46, v64, v46
	v_add_f32_e32 v46, v65, v46
	v_add_f32_e32 v46, v62, v46
	v_pk_mul_f32 v[14:15], v[36:37], v[36:37]
	v_add_f32_e32 v46, v63, v46
	v_add_f32_e32 v14, v14, v46
	v_add_f32_e32 v14, v15, v14
	v_add_f32_e32 v14, v66, v14
	v_pk_mul_f32 v[74:75], v[28:29], v[28:29]
	v_add_f32_e32 v14, v67, v14
	v_add_f32_e32 v14, v74, v14
	v_pk_mul_f32 v[72:73], v[30:31], v[30:31]
	v_add_f32_e32 v14, v75, v14
	v_add_f32_e32 v14, v72, v14
	v_pk_mul_f32 v[78:79], v[20:21], v[20:21]
	v_add_f32_e32 v14, v73, v14
	v_add_f32_e32 v14, v78, v14
	v_pk_mul_f32 v[76:77], v[22:23], v[22:23]
	v_add_f32_e32 v14, v79, v14
	v_add_f32_e32 v14, v76, v14
	v_pk_mul_f32 v[24:25], v[18:19], v[18:19]
	v_add_f32_e32 v14, v77, v14
	v_add_f32_e32 v14, v24, v14
	v_pk_mul_f32 v[26:27], v[16:17], v[16:17]
	v_add_f32_e32 v14, v25, v14
	v_add_f32_e32 v14, v26, v14
	v_add_f32_e32 v14, v27, v14
	v_add_f32_e32 v14, v50, v14
	v_add_f32_e32 v14, v51, v14
	v_add_f32_e32 v14, v52, v14
	v_add_f32_e32 v14, v53, v14
	v_mov_b32_e32 v15, v14
	s_nop 1
	v_permlane16_swap_b32_e32 v14, v15
	v_div_scale_f32 v81, s[22:23], v68, v68, v80
	v_rcp_f32_e32 v82, v81
	s_waitcnt lgkmcnt(0)
	v_add_f32_e32 v14, v14, v15
	v_mov_b32_e32 v15, v14
	s_nop 1
	v_permlane32_swap_b32_e32 v14, v15
	v_fma_f32 v24, -v81, v82, 1.0
	v_fmac_f32_e32 v82, v24, v82
	v_div_scale_f32 v24, vcc, v80, v68, v80
	s_waitcnt lgkmcnt(0)
	v_add_f32_e32 v14, v14, v15
	v_fmamk_f32 v14, v14, 0x3c000000, v231
	v_mul_f32_e32 v15, 0x4b800000, v14
	v_cmp_gt_f32_e64 s[4:5], s37, v14
	v_mul_f32_e32 v25, v24, v82
	v_fma_f32 v26, -v81, v25, v24
	v_cndmask_b32_e64 v14, v14, v15, s[4:5]
	v_rsq_f32_e32 v14, v14
	v_fmac_f32_e32 v25, v26, v82
	v_fma_f32 v24, -v81, v25, v24
	v_div_fmas_f32 v15, v24, v82, v25
	v_lshl_add_u64 v[24:25], v[10:11], 1, v[4:5]
	v_mul_f32_e32 v11, 0x45800000, v14
	v_cndmask_b32_e64 v14, v14, v11, s[4:5]
	v_pk_mul_f32 v[26:27], v[42:43], v[14:15] op_sel_hi:[1,0]
	v_div_fixup_f32 v46, v15, v68, v80
	s_waitcnt vmcnt(0)
	v_pk_mul_f32 v[0:1], v[0:1], v[26:27]
	v_pk_mul_f32 v[26:27], v[40:41], v[14:15] op_sel_hi:[1,0]
	v_pk_mul_f32 v[0:1], v[70:71], v[0:1]
	v_pk_mul_f32 v[2:3], v[2:3], v[26:27]
	v_cvt_pk_bf16_f32 v0, v0, v1
	v_pk_mul_f32 v[2:3], v[46:47], v[2:3]
	v_or_b32_e32 v40, s8, v124
	v_cvt_pk_bf16_f32 v1, v2, v3
	global_store_dwordx2 v[24:25], v[0:1], off
	v_mov_b64_e32 v[2:3], v[154:155]
	v_lshl_add_u64 v[0:1], s[8:9], 0, v[208:209]
	v_lshl_add_u64 v[0:1], v[0:1], 2, s[76:77]
	v_mov_b64_e32 v[24:25], v[168:169]
	v_mov_b64_e32 v[26:27], v[170:171]
	v_ashrrev_i32_e32 v41, 31, v40
	v_lshl_add_u64 v[40:41], v[40:41], 1, v[4:5]
	s_mov_b32 s76, s42
	v_lshlrev_b32_e32 v11, 16, v2
	v_and_b32_e32 v15, 0xffff0000, v2
	v_mul_f32_e32 v2, 0xbfb8aa3b, v11
	v_exp_f32_e32 v42, v2
	v_mul_f32_e32 v2, 0xbfb8aa3b, v15
	v_exp_f32_e32 v43, v2
	v_lshlrev_b32_e32 v50, 16, v3
	v_and_b32_e32 v51, 0xffff0000, v3
	v_pk_mul_f32 v[2:3], v[48:49], v[14:15] op_sel_hi:[1,0]
	v_pk_add_f32 v[42:43], v[42:43], 1.0 op_sel_hi:[1,0]
	v_pk_mul_f32 v[2:3], v[24:25], v[2:3]
	v_div_scale_f32 v46, s[4:5], v43, v43, v15
	v_rcp_f32_e32 v47, v46
	s_nop 0
	v_fma_f32 v24, -v46, v47, 1.0
	v_fmac_f32_e32 v47, v24, v47
	v_div_scale_f32 v24, vcc, v15, v43, v15
	v_mul_f32_e32 v25, v24, v47
	v_fma_f32 v48, -v46, v25, v24
	v_fmac_f32_e32 v25, v48, v47
	v_fma_f32 v24, -v46, v25, v24
	v_div_scale_f32 v46, s[4:5], v42, v42, v11
	v_rcp_f32_e32 v48, v46
	v_div_fmas_f32 v24, v24, v47, v25
	v_div_fixup_f32 v25, v24, v43, v15
	v_fma_f32 v15, -v46, v48, 1.0
	v_fmac_f32_e32 v48, v15, v48
	v_div_scale_f32 v15, vcc, v11, v42, v11
	v_mul_f32_e32 v24, v15, v48
	v_fma_f32 v43, -v46, v24, v15
	v_fmac_f32_e32 v24, v43, v48
	v_mul_f32_e32 v43, 0xbfb8aa3b, v50
	v_fma_f32 v15, -v46, v24, v15
	v_exp_f32_e32 v46, v43
	v_mul_f32_e32 v43, 0xbfb8aa3b, v51
	v_exp_f32_e32 v47, v43
	v_div_fmas_f32 v15, v15, v48, v24
	v_div_fixup_f32 v24, v15, v42, v11
	v_pk_mul_f32 v[2:3], v[24:25], v[2:3]
	v_pk_add_f32 v[24:25], v[46:47], 1.0 op_sel_hi:[1,0]
	v_cvt_pk_bf16_f32 v2, v2, v3
	v_div_scale_f32 v11, s[4:5], v25, v25, v51
	v_rcp_f32_e32 v15, v11
	s_nop 0
	v_fma_f32 v3, -v11, v15, 1.0
	v_pk_mul_f32 v[42:43], v[44:45], v[14:15] op_sel_hi:[1,0]
	v_fmac_f32_e32 v15, v3, v15
	v_div_scale_f32 v3, vcc, v51, v25, v51
	v_pk_mul_f32 v[26:27], v[26:27], v[42:43]
	v_mul_f32_e32 v42, v3, v15
	v_fma_f32 v43, -v11, v42, v3
	v_fmac_f32_e32 v42, v43, v15
	v_fma_f32 v3, -v11, v42, v3
	v_div_scale_f32 v11, s[4:5], v24, v24, v50
	v_rcp_f32_e32 v43, v11
	v_div_fmas_f32 v3, v3, v15, v42
	v_div_fixup_f32 v25, v3, v25, v51
	v_fma_f32 v3, -v11, v43, 1.0
	v_fmac_f32_e32 v43, v3, v43
	v_div_scale_f32 v3, vcc, v50, v24, v50
	v_mul_f32_e32 v15, v3, v43
	v_fma_f32 v42, -v11, v15, v3
	v_fmac_f32_e32 v15, v42, v43
	v_fma_f32 v3, -v11, v15, v3
	v_div_fmas_f32 v3, v3, v43, v15
	v_div_fixup_f32 v24, v3, v24, v50
	v_pk_mul_f32 v[24:25], v[24:25], v[26:27]
	v_pk_mul_f32 v[38:39], v[38:39], v[14:15] op_sel_hi:[1,0]
	v_cvt_pk_bf16_f32 v3, v24, v25
	global_store_dwordx2 v[40:41], v[2:3], off
	v_mov_b64_e32 v[2:3], v[156:157]
	s_nop 0
	v_mov_b64_e32 v[24:25], v[172:173]
	v_mov_b64_e32 v[26:27], v[174:175]
	v_or_b32_e32 v40, s8, v123
	v_ashrrev_i32_e32 v41, 31, v40
	v_lshl_add_u64 v[40:41], v[40:41], 1, v[4:5]
	v_lshlrev_b32_e32 v11, 16, v2
	v_and_b32_e32 v15, 0xffff0000, v2
	v_lshlrev_b32_e32 v42, 16, v3
	v_and_b32_e32 v43, 0xffff0000, v3
	v_pk_mul_f32 v[2:3], v[24:25], v[38:39]
	v_mul_f32_e32 v24, 0xbfb8aa3b, v11
	v_mul_f32_e32 v25, 0xbfb8aa3b, v15
	v_exp_f32_e32 v24, v24
	v_exp_f32_e32 v25, v25
	v_mul_f32_e32 v38, 0xbfb8aa3b, v42
	v_mul_f32_e32 v39, 0xbfb8aa3b, v43
	v_exp_f32_e32 v38, v38
	v_pk_add_f32 v[24:25], v[24:25], 1.0 op_sel_hi:[1,0]
	v_exp_f32_e32 v39, v39
	v_div_scale_f32 v44, s[4:5], v25, v25, v15
	v_div_scale_f32 v46, s[4:5], v24, v24, v11
	v_rcp_f32_e32 v47, v44
	v_rcp_f32_e32 v48, v46
	v_div_scale_f32 v45, vcc, v15, v25, v15
	v_fma_f32 v50, -v44, v47, 1.0
	v_fma_f32 v51, -v46, v48, 1.0
	v_fmac_f32_e32 v47, v50, v47
	v_div_scale_f32 v49, s[4:5], v11, v24, v11
	v_fmac_f32_e32 v48, v51, v48
	v_mul_f32_e32 v50, v45, v47
	v_mul_f32_e32 v51, v49, v48
	v_fma_f32 v52, -v44, v50, v45
	v_fma_f32 v53, -v46, v51, v49
	v_fmac_f32_e32 v50, v52, v47
	v_fmac_f32_e32 v51, v53, v48
	v_fma_f32 v44, -v44, v50, v45
	v_fma_f32 v45, -v46, v51, v49
	v_div_fmas_f32 v44, v44, v47, v50
	s_mov_b64 vcc, s[4:5]
	v_div_fixup_f32 v25, v44, v25, v15
	v_div_fmas_f32 v15, v45, v48, v51
	v_div_fixup_f32 v24, v15, v24, v11
	v_pk_mul_f32 v[2:3], v[24:25], v[2:3]
	v_pk_add_f32 v[24:25], v[38:39], 1.0 op_sel_hi:[1,0]
	v_cvt_pk_bf16_f32 v2, v2, v3
	v_div_scale_f32 v11, s[4:5], v25, v25, v43
	v_rcp_f32_e32 v15, v11
	s_nop 0
	v_fma_f32 v3, -v11, v15, 1.0
	v_pk_mul_f32 v[34:35], v[34:35], v[14:15] op_sel_hi:[1,0]
	v_fmac_f32_e32 v15, v3, v15
	v_div_scale_f32 v3, vcc, v43, v25, v43
	v_pk_mul_f32 v[26:27], v[26:27], v[34:35]
	v_mul_f32_e32 v34, v3, v15
	v_fma_f32 v35, -v11, v34, v3
	v_fmac_f32_e32 v34, v35, v15
	v_fma_f32 v3, -v11, v34, v3
	v_div_scale_f32 v11, s[4:5], v24, v24, v42
	v_rcp_f32_e32 v35, v11
	v_div_fmas_f32 v3, v3, v15, v34
	v_div_fixup_f32 v25, v3, v25, v43
	v_fma_f32 v3, -v11, v35, 1.0
	v_fmac_f32_e32 v35, v3, v35
	v_div_scale_f32 v3, vcc, v42, v24, v42
	v_mul_f32_e32 v15, v3, v35
	v_fma_f32 v34, -v11, v15, v3
	v_fmac_f32_e32 v15, v34, v35
	v_fma_f32 v3, -v11, v15, v3
	v_div_fmas_f32 v3, v3, v35, v15
	v_div_fixup_f32 v24, v3, v24, v42
	v_pk_mul_f32 v[24:25], v[24:25], v[26:27]
	v_pk_mul_f32 v[36:37], v[36:37], v[14:15] op_sel_hi:[1,0]
	v_cvt_pk_bf16_f32 v3, v24, v25
	global_store_dwordx2 v[40:41], v[2:3], off
	v_mov_b64_e32 v[2:3], v[158:159]
	s_nop 0
	v_mov_b64_e32 v[24:25], v[176:177]
	v_mov_b64_e32 v[26:27], v[178:179]
	v_pk_mul_f32 v[32:33], v[32:33], v[14:15] op_sel_hi:[1,0]
	v_or_b32_e32 v34, s8, v122
	v_ashrrev_i32_e32 v35, 31, v34
	v_lshl_add_u64 v[34:35], v[34:35], 1, v[4:5]
	v_lshlrev_b32_e32 v11, 16, v2
	v_and_b32_e32 v15, 0xffff0000, v2
	v_lshlrev_b32_e32 v40, 16, v3
	v_and_b32_e32 v41, 0xffff0000, v3
	v_mul_f32_e32 v2, 0xbfb8aa3b, v11
	v_mul_f32_e32 v3, 0xbfb8aa3b, v15
	v_exp_f32_e32 v2, v2
	v_exp_f32_e32 v3, v3
	v_mul_f32_e32 v38, 0xbfb8aa3b, v40
	v_mul_f32_e32 v39, 0xbfb8aa3b, v41
	v_exp_f32_e32 v38, v38
	v_exp_f32_e32 v39, v39
	v_pk_add_f32 v[2:3], v[2:3], 1.0 op_sel_hi:[1,0]
	v_pk_mul_f32 v[24:25], v[24:25], v[36:37]
	v_div_scale_f32 v36, s[4:5], v3, v3, v15
	v_pk_mul_f32 v[26:27], v[26:27], v[32:33]
	v_pk_add_f32 v[32:33], v[38:39], 1.0 op_sel_hi:[1,0]
	v_div_scale_f32 v38, s[4:5], v2, v2, v11
	v_rcp_f32_e32 v45, v36
	v_rcp_f32_e32 v46, v38
	v_div_scale_f32 v42, s[6:7], v33, v33, v41
	v_rcp_f32_e32 v47, v42
	v_fma_f32 v49, -v36, v45, 1.0
	v_div_scale_f32 v37, vcc, v15, v3, v15
	v_fma_f32 v50, -v38, v46, 1.0
	v_fmac_f32_e32 v45, v49, v45
	v_div_scale_f32 v39, s[4:5], v11, v2, v11
	v_fmac_f32_e32 v46, v50, v46
	v_mul_f32_e32 v49, v37, v45
	v_mul_f32_e32 v50, v39, v46
	v_fma_f32 v53, -v36, v49, v37
	v_div_scale_f32 v44, s[8:9], v32, v32, v40
	v_fma_f32 v51, -v42, v47, 1.0
	v_fma_f32 v54, -v38, v50, v39
	v_fmac_f32_e32 v49, v53, v45
	v_div_scale_f32 v43, s[6:7], v41, v33, v41
	v_rcp_f32_e32 v48, v44
	v_fmac_f32_e32 v47, v51, v47
	v_fmac_f32_e32 v50, v54, v46
	v_fma_f32 v36, -v36, v49, v37
	v_mul_f32_e32 v51, v43, v47
	v_fma_f32 v37, -v38, v50, v39
	v_div_fmas_f32 v36, v36, v45, v49
	s_mov_b64 vcc, s[4:5]
	v_fma_f32 v55, -v42, v51, v43
	v_div_fixup_f32 v3, v36, v3, v15
	v_div_fmas_f32 v15, v37, v46, v50
	v_fmac_f32_e32 v51, v55, v47
	v_div_fixup_f32 v2, v15, v2, v11
	v_fma_f32 v52, -v44, v48, 1.0
	v_fma_f32 v38, -v42, v51, v43
	s_mov_b64 vcc, s[6:7]
	v_pk_mul_f32 v[2:3], v[2:3], v[24:25]
	v_div_fmas_f32 v11, v38, v47, v51
	v_cvt_pk_bf16_f32 v2, v2, v3
	v_fmac_f32_e32 v48, v52, v48
	v_div_scale_f32 v3, vcc, v40, v32, v40
	v_div_fixup_f32 v25, v11, v33, v41
	v_mul_f32_e32 v11, v3, v48
	v_fma_f32 v15, -v44, v11, v3
	v_fmac_f32_e32 v11, v15, v48
	v_fma_f32 v3, -v44, v11, v3
	v_div_fmas_f32 v3, v3, v48, v11
	v_div_fixup_f32 v24, v3, v32, v40
	v_pk_mul_f32 v[24:25], v[24:25], v[26:27]
	v_pk_mul_f32 v[28:29], v[28:29], v[14:15] op_sel_hi:[1,0]
	v_cvt_pk_bf16_f32 v3, v24, v25
	global_store_dwordx2 v[34:35], v[2:3], off
	v_mov_b64_e32 v[2:3], v[160:161]
	s_nop 0
	v_mov_b64_e32 v[24:25], v[180:181]
	v_mov_b64_e32 v[26:27], v[182:183]
	v_pk_mul_f32 v[30:31], v[30:31], v[14:15] op_sel_hi:[1,0]
	v_or_b32_e32 v32, 64, v10
	v_ashrrev_i32_e32 v33, 31, v32
	v_lshl_add_u64 v[32:33], v[32:33], 1, v[4:5]
	v_lshlrev_b32_e32 v11, 16, v2
	v_and_b32_e32 v15, 0xffff0000, v2
	v_lshlrev_b32_e32 v36, 16, v3
	v_and_b32_e32 v37, 0xffff0000, v3
	v_mul_f32_e32 v2, 0xbfb8aa3b, v11
	v_mul_f32_e32 v3, 0xbfb8aa3b, v15
	v_exp_f32_e32 v2, v2
	v_exp_f32_e32 v3, v3
	v_mul_f32_e32 v34, 0xbfb8aa3b, v36
	v_mul_f32_e32 v35, 0xbfb8aa3b, v37
	v_exp_f32_e32 v34, v34
	v_exp_f32_e32 v35, v35
	v_pk_add_f32 v[2:3], v[2:3], 1.0 op_sel_hi:[1,0]
	v_pk_mul_f32 v[26:27], v[26:27], v[30:31]
	v_div_scale_f32 v30, s[4:5], v3, v3, v15
	v_pk_mul_f32 v[24:25], v[24:25], v[28:29]
	v_pk_add_f32 v[28:29], v[34:35], 1.0 op_sel_hi:[1,0]
	v_div_scale_f32 v34, s[4:5], v2, v2, v11
	v_rcp_f32_e32 v42, v30
	v_div_scale_f32 v38, s[6:7], v29, v29, v37
	v_rcp_f32_e32 v43, v34
	v_div_scale_f32 v40, s[8:9], v28, v28, v36
	v_rcp_f32_e32 v44, v38
	v_rcp_f32_e32 v45, v40
	v_fma_f32 v46, -v30, v42, 1.0
	v_div_scale_f32 v31, vcc, v15, v3, v15
	v_fma_f32 v47, -v34, v43, 1.0
	v_fmac_f32_e32 v42, v46, v42
	v_div_scale_f32 v35, s[4:5], v11, v2, v11
	v_fma_f32 v48, -v38, v44, 1.0
	v_fmac_f32_e32 v43, v47, v43
	v_mul_f32_e32 v46, v31, v42
	v_div_scale_f32 v39, s[6:7], v37, v29, v37
	v_fma_f32 v49, -v40, v45, 1.0
	v_fmac_f32_e32 v44, v48, v44
	v_mul_f32_e32 v47, v35, v43
	v_fma_f32 v50, -v30, v46, v31
	v_div_scale_f32 v41, s[8:9], v36, v28, v36
	v_fmac_f32_e32 v45, v49, v45
	v_mul_f32_e32 v48, v39, v44
	v_fma_f32 v51, -v34, v47, v35
	v_fmac_f32_e32 v46, v50, v42
	v_mul_f32_e32 v49, v41, v45
	v_fma_f32 v52, -v38, v48, v39
	v_fmac_f32_e32 v47, v51, v43
	v_fma_f32 v30, -v30, v46, v31
	v_fma_f32 v53, -v40, v49, v41
	v_fmac_f32_e32 v48, v52, v44
	v_fma_f32 v31, -v34, v47, v35
	v_div_fmas_f32 v30, v30, v42, v46
	s_mov_b64 vcc, s[4:5]
	v_fmac_f32_e32 v49, v53, v45
	v_fma_f32 v34, -v38, v48, v39
	v_div_fixup_f32 v3, v30, v3, v15
	v_div_fmas_f32 v15, v31, v43, v47
	s_mov_b64 vcc, s[6:7]
	v_fma_f32 v35, -v40, v49, v41
	v_div_fixup_f32 v2, v15, v2, v11
	v_div_fmas_f32 v11, v34, v44, v48
	s_mov_b64 vcc, s[8:9]
	v_pk_mul_f32 v[2:3], v[2:3], v[24:25]
	v_div_fixup_f32 v25, v11, v29, v37
	v_div_fmas_f32 v11, v35, v45, v49
	v_div_fixup_f32 v24, v11, v28, v36
	v_pk_mul_f32 v[24:25], v[24:25], v[26:27]
	v_cvt_pk_bf16_f32 v2, v2, v3
	v_cvt_pk_bf16_f32 v3, v24, v25
	global_store_dwordx2 v[32:33], v[2:3], off
	v_mov_b64_e32 v[2:3], v[162:163]
	s_nop 0
	v_mov_b64_e32 v[24:25], v[184:185]
	v_mov_b64_e32 v[26:27], v[186:187]
	v_pk_mul_f32 v[20:21], v[20:21], v[14:15] op_sel_hi:[1,0]
	v_pk_mul_f32 v[22:23], v[22:23], v[14:15] op_sel_hi:[1,0]
	v_or_b32_e32 v28, 0x50, v10
	v_ashrrev_i32_e32 v29, 31, v28
	v_lshl_add_u64 v[28:29], v[28:29], 1, v[4:5]
	v_lshlrev_b32_e32 v11, 16, v2
	v_and_b32_e32 v15, 0xffff0000, v2
	v_lshlrev_b32_e32 v32, 16, v3
	v_and_b32_e32 v33, 0xffff0000, v3
	v_mul_f32_e32 v2, 0xbfb8aa3b, v11
	v_mul_f32_e32 v3, 0xbfb8aa3b, v15
	v_exp_f32_e32 v2, v2
	v_exp_f32_e32 v3, v3
	v_mul_f32_e32 v30, 0xbfb8aa3b, v32
	v_mul_f32_e32 v31, 0xbfb8aa3b, v33
	v_exp_f32_e32 v30, v30
	v_exp_f32_e32 v31, v31
	v_pk_add_f32 v[2:3], v[2:3], 1.0 op_sel_hi:[1,0]
	v_pk_mul_f32 v[22:23], v[26:27], v[22:23]
	v_div_scale_f32 v26, s[4:5], v3, v3, v15
	v_pk_mul_f32 v[20:21], v[24:25], v[20:21]
	v_pk_add_f32 v[24:25], v[30:31], 1.0 op_sel_hi:[1,0]
	v_div_scale_f32 v30, s[4:5], v2, v2, v11
	v_rcp_f32_e32 v38, v26
	v_div_scale_f32 v34, s[6:7], v25, v25, v33
	v_rcp_f32_e32 v39, v30
	v_div_scale_f32 v36, s[8:9], v24, v24, v32
	v_rcp_f32_e32 v40, v34
	v_rcp_f32_e32 v41, v36
	v_fma_f32 v42, -v26, v38, 1.0
	v_div_scale_f32 v27, vcc, v15, v3, v15
	v_fma_f32 v43, -v30, v39, 1.0
	v_fmac_f32_e32 v38, v42, v38
	v_div_scale_f32 v31, s[4:5], v11, v2, v11
	v_fma_f32 v44, -v34, v40, 1.0
	v_fmac_f32_e32 v39, v43, v39
	v_mul_f32_e32 v42, v27, v38
	v_div_scale_f32 v35, s[6:7], v33, v25, v33
	v_fma_f32 v45, -v36, v41, 1.0
	v_fmac_f32_e32 v40, v44, v40
	v_mul_f32_e32 v43, v31, v39
	v_fma_f32 v46, -v26, v42, v27
	v_div_scale_f32 v37, s[8:9], v32, v24, v32
	v_fmac_f32_e32 v41, v45, v41
	v_mul_f32_e32 v44, v35, v40
	v_fma_f32 v47, -v30, v43, v31
	v_fmac_f32_e32 v42, v46, v38
	v_mul_f32_e32 v45, v37, v41
	v_fma_f32 v48, -v34, v44, v35
	v_fmac_f32_e32 v43, v47, v39
	v_fma_f32 v26, -v26, v42, v27
	v_fma_f32 v49, -v36, v45, v37
	v_fmac_f32_e32 v44, v48, v40
	v_fma_f32 v27, -v30, v43, v31
	v_div_fmas_f32 v26, v26, v38, v42
	s_mov_b64 vcc, s[4:5]
	v_fmac_f32_e32 v45, v49, v41
	v_fma_f32 v30, -v34, v44, v35
	v_div_fixup_f32 v3, v26, v3, v15
	v_div_fmas_f32 v15, v27, v39, v43
	s_mov_b64 vcc, s[6:7]
	v_fma_f32 v31, -v36, v45, v37
	v_div_fixup_f32 v2, v15, v2, v11
	v_div_fmas_f32 v11, v30, v40, v44
	s_mov_b64 vcc, s[8:9]
	v_pk_mul_f32 v[2:3], v[2:3], v[20:21]
	v_div_fixup_f32 v21, v11, v25, v33
	v_div_fmas_f32 v11, v31, v41, v45
	v_div_fixup_f32 v20, v11, v24, v32
	v_pk_mul_f32 v[20:21], v[20:21], v[22:23]
	v_cvt_pk_bf16_f32 v2, v2, v3
	v_cvt_pk_bf16_f32 v3, v20, v21
	global_store_dwordx2 v[28:29], v[2:3], off
	v_mov_b64_e32 v[2:3], v[164:165]
	s_nop 0
	v_mov_b64_e32 v[20:21], v[188:189]
	v_mov_b64_e32 v[22:23], v[190:191]
	v_pk_mul_f32 v[18:19], v[18:19], v[14:15] op_sel_hi:[1,0]
	v_pk_mul_f32 v[16:17], v[16:17], v[14:15] op_sel_hi:[1,0]
	v_or_b32_e32 v24, 0x60, v10
	v_ashrrev_i32_e32 v25, 31, v24
	v_lshl_add_u64 v[24:25], v[24:25], 1, v[4:5]
	v_or_b32_e32 v10, 0x70, v10
	v_lshlrev_b32_e32 v11, 16, v2
	v_and_b32_e32 v15, 0xffff0000, v2
	v_lshlrev_b32_e32 v28, 16, v3
	v_and_b32_e32 v29, 0xffff0000, v3
	v_mul_f32_e32 v2, 0xbfb8aa3b, v11
	v_mul_f32_e32 v3, 0xbfb8aa3b, v15
	v_exp_f32_e32 v2, v2
	v_exp_f32_e32 v3, v3
	v_mul_f32_e32 v26, 0xbfb8aa3b, v28
	v_mul_f32_e32 v27, 0xbfb8aa3b, v29
	v_exp_f32_e32 v26, v26
	v_exp_f32_e32 v27, v27
	v_pk_add_f32 v[2:3], v[2:3], 1.0 op_sel_hi:[1,0]
	v_pk_mul_f32 v[16:17], v[22:23], v[16:17]
	v_div_scale_f32 v22, s[4:5], v3, v3, v15
	v_pk_mul_f32 v[18:19], v[20:21], v[18:19]
	v_pk_add_f32 v[20:21], v[26:27], 1.0 op_sel_hi:[1,0]
	v_div_scale_f32 v26, s[4:5], v2, v2, v11
	v_rcp_f32_e32 v34, v22
	v_div_scale_f32 v30, s[6:7], v21, v21, v29
	v_rcp_f32_e32 v35, v26
	v_div_scale_f32 v32, s[8:9], v20, v20, v28
	v_rcp_f32_e32 v36, v30
	v_rcp_f32_e32 v37, v32
	v_fma_f32 v38, -v22, v34, 1.0
	v_div_scale_f32 v23, vcc, v15, v3, v15
	v_fma_f32 v39, -v26, v35, 1.0
	v_fmac_f32_e32 v34, v38, v34
	v_div_scale_f32 v27, s[4:5], v11, v2, v11
	v_fma_f32 v40, -v30, v36, 1.0
	v_fmac_f32_e32 v35, v39, v35
	v_mul_f32_e32 v38, v23, v34
	v_div_scale_f32 v31, s[6:7], v29, v21, v29
	v_fma_f32 v41, -v32, v37, 1.0
	v_fmac_f32_e32 v36, v40, v36
	v_mul_f32_e32 v39, v27, v35
	v_fma_f32 v42, -v22, v38, v23
	v_div_scale_f32 v33, s[8:9], v28, v20, v28
	v_fmac_f32_e32 v37, v41, v37
	v_mul_f32_e32 v40, v31, v36
	v_fma_f32 v43, -v26, v39, v27
	v_fmac_f32_e32 v38, v42, v34
	v_mul_f32_e32 v41, v33, v37
	v_fma_f32 v44, -v30, v40, v31
	v_fmac_f32_e32 v39, v43, v35
	v_fma_f32 v22, -v22, v38, v23
	v_fma_f32 v45, -v32, v41, v33
	v_fmac_f32_e32 v40, v44, v36
	v_fma_f32 v23, -v26, v39, v27
	v_div_fmas_f32 v22, v22, v34, v38
	s_mov_b64 vcc, s[4:5]
	v_fmac_f32_e32 v41, v45, v37
	v_fma_f32 v26, -v30, v40, v31
	v_div_fixup_f32 v3, v22, v3, v15
	v_div_fmas_f32 v15, v23, v35, v39
	s_mov_b64 vcc, s[6:7]
	v_fma_f32 v27, -v32, v41, v33
	v_div_fixup_f32 v2, v15, v2, v11
	v_div_fmas_f32 v11, v26, v36, v40
	s_mov_b64 vcc, s[8:9]
	v_pk_mul_f32 v[2:3], v[2:3], v[18:19]
	v_div_fixup_f32 v19, v11, v21, v29
	v_div_fmas_f32 v11, v27, v37, v41
	v_div_fixup_f32 v18, v11, v20, v28
	v_pk_mul_f32 v[16:17], v[18:19], v[16:17]
	v_cvt_pk_bf16_f32 v2, v2, v3
	v_cvt_pk_bf16_f32 v3, v16, v17
	global_store_dwordx2 v[24:25], v[2:3], off
	v_mov_b64_e32 v[8:9], v[166:167]
	s_nop 0
	v_mov_b64_e32 v[0:1], v[192:193]
	v_mov_b64_e32 v[2:3], v[194:195]
	v_pk_mul_f32 v[12:13], v[12:13], v[14:15] op_sel_hi:[1,0]
	v_pk_mul_f32 v[6:7], v[6:7], v[14:15] op_sel_hi:[1,0]
	v_ashrrev_i32_e32 v11, 31, v10
	v_lshlrev_b32_e32 v16, 16, v8
	v_and_b32_e32 v17, 0xffff0000, v8
	v_lshlrev_b32_e32 v18, 16, v9
	v_and_b32_e32 v19, 0xffff0000, v9
	v_mul_f32_e32 v8, 0xbfb8aa3b, v16
	v_mul_f32_e32 v9, 0xbfb8aa3b, v17
	v_exp_f32_e32 v8, v8
	v_exp_f32_e32 v9, v9
	v_mul_f32_e32 v14, 0xbfb8aa3b, v18
	v_mul_f32_e32 v15, 0xbfb8aa3b, v19
	v_exp_f32_e32 v14, v14
	v_exp_f32_e32 v15, v15
	v_pk_mul_f32 v[2:3], v[2:3], v[6:7]
	v_pk_add_f32 v[6:7], v[8:9], 1.0 op_sel_hi:[1,0]
	v_pk_mul_f32 v[0:1], v[0:1], v[12:13]
	v_div_scale_f32 v12, s[4:5], v7, v7, v17
	v_pk_add_f32 v[8:9], v[14:15], 1.0 op_sel_hi:[1,0]
	v_div_scale_f32 v14, s[4:5], v6, v6, v16
	v_rcp_f32_e32 v24, v12
	v_div_scale_f32 v20, s[6:7], v9, v9, v19
	v_rcp_f32_e32 v25, v14
	v_div_scale_f32 v22, s[8:9], v8, v8, v18
	v_rcp_f32_e32 v26, v20
	v_rcp_f32_e32 v27, v22
	v_fma_f32 v28, -v12, v24, 1.0
	v_div_scale_f32 v13, vcc, v17, v7, v17
	v_fma_f32 v29, -v14, v25, 1.0
	v_fmac_f32_e32 v24, v28, v24
	v_div_scale_f32 v15, s[4:5], v16, v6, v16
	v_fma_f32 v30, -v20, v26, 1.0
	v_fmac_f32_e32 v25, v29, v25
	v_mul_f32_e32 v28, v13, v24
	v_div_scale_f32 v21, s[6:7], v19, v9, v19
	v_fma_f32 v31, -v22, v27, 1.0
	v_fmac_f32_e32 v26, v30, v26
	v_mul_f32_e32 v29, v15, v25
	v_fma_f32 v32, -v12, v28, v13
	v_div_scale_f32 v23, s[8:9], v18, v8, v18
	v_fmac_f32_e32 v27, v31, v27
	v_mul_f32_e32 v30, v21, v26
	v_fma_f32 v33, -v14, v29, v15
	v_fmac_f32_e32 v28, v32, v24
	v_mul_f32_e32 v31, v23, v27
	v_fma_f32 v34, -v20, v30, v21
	v_fmac_f32_e32 v29, v33, v25
	v_fma_f32 v12, -v12, v28, v13
	v_fma_f32 v35, -v22, v31, v23
	v_fmac_f32_e32 v30, v34, v26
	v_fma_f32 v13, -v14, v29, v15
	v_div_fmas_f32 v12, v12, v24, v28
	s_mov_b64 vcc, s[4:5]
	v_fmac_f32_e32 v31, v35, v27
	v_fma_f32 v14, -v20, v30, v21
	v_div_fixup_f32 v7, v12, v7, v17
	v_div_fmas_f32 v12, v13, v25, v29
	s_mov_b64 vcc, s[6:7]
	v_fma_f32 v15, -v22, v31, v23
	v_div_fixup_f32 v6, v12, v6, v16
	v_div_fmas_f32 v12, v14, v26, v30
	s_mov_b64 vcc, s[8:9]
	v_pk_mul_f32 v[0:1], v[6:7], v[0:1]
	v_div_fmas_f32 v6, v15, v27, v31
	v_div_fixup_f32 v7, v12, v9, v19
	v_div_fixup_f32 v6, v6, v8, v18
	v_pk_mul_f32 v[2:3], v[6:7], v[2:3]
	v_cvt_pk_bf16_f32 v0, v0, v1
	v_cvt_pk_bf16_f32 v1, v2, v3
	v_lshl_add_u64 v[2:3], v[10:11], 1, v[4:5]
	global_store_dwordx2 v[2:3], v[0:1], off

.LBB0_1100:
	s_load_dwordx2 s[4:5], s[82:83], 0x40
	v_lshlrev_b32_e32 v0, 1, v208
	v_mov_b32_e32 v1, v209
	v_or_b32_e32 v12, s8, v208
	v_ashrrev_i32_e32 v13, 31, v12
	s_waitcnt lgkmcnt(0)
	s_add_u32 s76, s4, s14
	s_addc_u32 s77, s5, s15
	s_add_i32 s4, s8, 0x1000
	s_ashr_i32 s4, s4, 7
	s_ashr_i32 s5, s4, 31
	s_lshl_b64 s[4:5], s[4:5], 21
	s_add_u32 s4, s80, s4
	s_addc_u32 s5, s81, s5
	v_lshl_add_u64 v[2:3], s[4:5], 0, v[98:99]
	v_lshl_add_u64 v[10:11], v[2:3], 0, v[0:1]
	global_load_dwordx2 v[14:15], v[10:11], off
	v_mov_b32_e32 v2, v135
	s_nop 1
	v_permlane16_swap_b32_e32 v135, v2
	v_lshlrev_b64 v[0:1], 12, v[96:97]
	v_lshl_add_u64 v[0:1], s[56:57], 0, v[0:1]
	v_lshl_add_u64 v[4:5], v[0:1], 0, s[68:69]
	v_lshl_add_u64 v[0:1], v[12:13], 2, s[76:77]
	s_waitcnt lgkmcnt(0)
	v_add_f32_e32 v2, v135, v2
	v_mov_b32_e32 v3, v2
	s_nop 1
	v_permlane32_swap_b32_e32 v2, v3
	s_ashr_i32 s9, s8, 31
	s_mov_b32 s86, s46
	s_waitcnt lgkmcnt(0)
	v_add_f32_e32 v6, v2, v3
	v_div_scale_f32 v7, s[4:5], v6, v6, 1.0
	v_rcp_f32_e32 v8, v7
	v_div_scale_f32 v9, vcc, 1.0, v6, 1.0
	global_load_dwordx2 v[154:155], v[10:11], off offset:32
	global_load_dwordx2 v[156:157], v[10:11], off offset:64
	global_load_dwordx2 v[158:159], v[10:11], off offset:96
	global_load_dwordx2 v[160:161], v[10:11], off offset:128
	global_load_dwordx2 v[162:163], v[10:11], off offset:160
	global_load_dwordx2 v[164:165], v[10:11], off offset:192
	global_load_dwordx2 v[166:167], v[10:11], off offset:224
	global_load_dwordx4 v[168:171], v[0:1], off offset:64
	global_load_dwordx4 v[172:175], v[0:1], off offset:128
	global_load_dwordx4 v[176:179], v[0:1], off offset:192
	global_load_dwordx4 v[180:183], v[0:1], off offset:256
	global_load_dwordx4 v[184:187], v[0:1], off offset:320
	global_load_dwordx4 v[188:191], v[0:1], off offset:384
	global_load_dwordx4 v[192:195], v[0:1], off offset:448
	global_load_dwordx4 v[0:3], v[0:1], off
	s_waitcnt vmcnt(8)
	v_fma_f32 v32, -v7, v8, 1.0
	v_fmac_f32_e32 v8, v32, v8
	v_mul_f32_e32 v32, v9, v8
	v_fma_f32 v33, -v7, v32, v9
	v_fmac_f32_e32 v32, v33, v8
	v_fma_f32 v7, -v7, v32, v9
	v_div_fmas_f32 v7, v7, v8, v32
	s_waitcnt vmcnt(6)
	v_div_fixup_f32 v46, v7, v6, 1.0
	v_pk_mul_f32 v[6:7], v[76:77], v[46:47] op_sel_hi:[1,0]
	v_pk_mul_f32 v[8:9], v[78:79], v[46:47] op_sel_hi:[1,0]
	v_pk_mul_f32 v[40:41], v[74:75], v[46:47] op_sel_hi:[1,0]
	v_pk_mul_f32 v[42:43], v[72:73], v[46:47] op_sel_hi:[1,0]
	v_pk_mul_f32 v[44:45], v[70:71], v[46:47] op_sel_hi:[1,0]
	s_waitcnt vmcnt(5)
	v_pk_mul_f32 v[48:49], v[68:69], v[46:47] op_sel_hi:[1,0]
	v_pk_mul_f32 v[34:35], v[58:59], v[46:47] op_sel_hi:[1,0]
	v_pk_mul_f32 v[38:39], v[56:57], v[46:47] op_sel_hi:[1,0]
	v_pk_mul_f32 v[32:33], v[18:19], v[46:47] op_sel_hi:[1,0]
	v_pk_mul_f32 v[56:57], v[42:43], v[42:43]
	s_waitcnt vmcnt(4)
	v_pk_mul_f32 v[54:55], v[40:41], v[40:41]
	s_waitcnt vmcnt(3)
	v_pk_mul_f32 v[60:61], v[48:49], v[48:49]
	v_pk_mul_f32 v[58:59], v[44:45], v[44:45]
	s_waitcnt vmcnt(2)
	v_pk_mul_f32 v[64:65], v[38:39], v[38:39]
	v_pk_mul_f32 v[62:63], v[34:35], v[34:35]
	v_pk_mul_f32 v[66:67], v[32:33], v[32:33]
	v_pk_mul_f32 v[50:51], v[6:7], v[6:7]
	v_pk_mul_f32 v[52:53], v[8:9], v[8:9]
	s_waitcnt vmcnt(1)
	v_lshlrev_b32_e32 v37, 16, v14
	v_and_b32_e32 v47, 0xffff0000, v14
	v_lshlrev_b32_e32 v80, 16, v15
	v_and_b32_e32 v36, 0xffff0000, v15
	v_mul_f32_e32 v14, 0xbfb8aa3b, v37
	v_mul_f32_e32 v15, 0xbfb8aa3b, v47
	v_mul_f32_e32 v18, 0xbfb8aa3b, v80
	v_mul_f32_e32 v19, 0xbfb8aa3b, v36
	v_exp_f32_e32 v14, v14
	v_exp_f32_e32 v15, v15
	v_exp_f32_e32 v18, v18
	v_exp_f32_e32 v19, v19
	v_pk_add_f32 v[14:15], v[14:15], 1.0 op_sel_hi:[1,0]
	s_nop 0
	v_div_scale_f32 v70, s[4:5], v14, v14, v37
	v_pk_add_f32 v[68:69], v[18:19], 1.0 op_sel_hi:[1,0]
	v_div_scale_f32 v18, s[4:5], v15, v15, v47
	v_rcp_f32_e32 v74, v18
	v_div_scale_f32 v72, s[6:7], v69, v69, v36
	v_rcp_f32_e32 v75, v70
	v_rcp_f32_e32 v76, v72
	v_fma_f32 v77, -v18, v74, 1.0
	v_div_scale_f32 v19, vcc, v47, v15, v47
	v_fma_f32 v78, -v70, v75, 1.0
	v_fmac_f32_e32 v74, v77, v74
	v_div_scale_f32 v71, s[4:5], v37, v14, v37
	v_fma_f32 v79, -v72, v76, 1.0
	v_fmac_f32_e32 v75, v78, v75
	v_mul_f32_e32 v77, v19, v74
	v_div_scale_f32 v73, s[6:7], v36, v69, v36
	v_fmac_f32_e32 v76, v79, v76
	v_mul_f32_e32 v78, v71, v75
	v_fma_f32 v83, -v18, v77, v19
	v_mul_f32_e32 v79, v73, v76
	v_fma_f32 v84, -v70, v78, v71
	v_fmac_f32_e32 v77, v83, v74
	v_fma_f32 v85, -v72, v79, v73
	v_fmac_f32_e32 v78, v84, v75
	v_fma_f32 v18, -v18, v77, v19
	v_fmac_f32_e32 v79, v85, v76
	v_fma_f32 v19, -v70, v78, v71
	v_div_fmas_f32 v18, v18, v74, v77
	s_mov_b64 vcc, s[4:5]
	v_fma_f32 v72, -v72, v79, v73
	v_div_fixup_f32 v71, v18, v15, v47
	v_div_fmas_f32 v15, v19, v75, v78
	s_mov_b64 vcc, s[6:7]
	v_div_fixup_f32 v70, v15, v14, v37
	v_div_fmas_f32 v14, v72, v76, v79
	v_div_fixup_f32 v47, v14, v69, v36
	v_pk_mul_f32 v[36:37], v[16:17], v[46:47] op_sel_hi:[1,0]
	v_pk_mul_f32 v[30:31], v[30:31], v[46:47] op_sel_hi:[1,0]
	v_pk_mul_f32 v[28:29], v[28:29], v[46:47] op_sel_hi:[1,0]
	v_pk_mul_f32 v[22:23], v[22:23], v[46:47] op_sel_hi:[1,0]
	v_pk_mul_f32 v[20:21], v[20:21], v[46:47] op_sel_hi:[1,0]
	v_pk_mul_f32 v[16:17], v[26:27], v[46:47] op_sel_hi:[1,0]
	v_pk_mul_f32 v[18:19], v[24:25], v[46:47] op_sel_hi:[1,0]
	v_add_f32_e32 v46, v56, v57
	v_add_f32_e32 v46, v54, v46
	v_add_f32_e32 v46, v55, v46
	v_add_f32_e32 v46, v60, v46
	v_add_f32_e32 v46, v61, v46
	v_add_f32_e32 v46, v58, v46
	v_add_f32_e32 v46, v59, v46
	v_add_f32_e32 v46, v64, v46
	v_add_f32_e32 v46, v65, v46
	v_add_f32_e32 v46, v62, v46
	v_pk_mul_f32 v[14:15], v[36:37], v[36:37]
	v_add_f32_e32 v46, v63, v46
	v_add_f32_e32 v14, v14, v46
	v_add_f32_e32 v14, v15, v14
	v_add_f32_e32 v14, v66, v14
	v_pk_mul_f32 v[74:75], v[28:29], v[28:29]
	v_add_f32_e32 v14, v67, v14
	v_add_f32_e32 v14, v74, v14
	v_pk_mul_f32 v[72:73], v[30:31], v[30:31]
	v_add_f32_e32 v14, v75, v14
	v_add_f32_e32 v14, v72, v14
	v_pk_mul_f32 v[78:79], v[20:21], v[20:21]
	v_add_f32_e32 v14, v73, v14
	v_add_f32_e32 v14, v78, v14
	v_pk_mul_f32 v[76:77], v[22:23], v[22:23]
	v_add_f32_e32 v14, v79, v14
	v_add_f32_e32 v14, v76, v14
	v_pk_mul_f32 v[24:25], v[18:19], v[18:19]
	v_add_f32_e32 v14, v77, v14
	v_add_f32_e32 v14, v24, v14
	v_pk_mul_f32 v[26:27], v[16:17], v[16:17]
	v_add_f32_e32 v14, v25, v14
	v_add_f32_e32 v14, v26, v14
	v_add_f32_e32 v14, v27, v14
	v_add_f32_e32 v14, v50, v14
	v_add_f32_e32 v14, v51, v14
	v_add_f32_e32 v14, v52, v14
	v_add_f32_e32 v14, v53, v14
	v_mov_b32_e32 v15, v14
	s_nop 1
	v_permlane16_swap_b32_e32 v14, v15
	v_div_scale_f32 v81, s[22:23], v68, v68, v80
	v_rcp_f32_e32 v82, v81
	s_waitcnt lgkmcnt(0)
	v_add_f32_e32 v14, v14, v15
	v_mov_b32_e32 v15, v14
	s_nop 1
	v_permlane32_swap_b32_e32 v14, v15
	v_fma_f32 v24, -v81, v82, 1.0
	v_fmac_f32_e32 v82, v24, v82
	v_div_scale_f32 v24, vcc, v80, v68, v80
	s_waitcnt lgkmcnt(0)
	v_add_f32_e32 v14, v14, v15
	v_fmamk_f32 v14, v14, 0x3c000000, v231
	v_mul_f32_e32 v15, 0x4b800000, v14
	v_cmp_gt_f32_e64 s[4:5], s37, v14
	v_mul_f32_e32 v25, v24, v82
	v_fma_f32 v26, -v81, v25, v24
	v_cndmask_b32_e64 v14, v14, v15, s[4:5]
	v_rsq_f32_e32 v14, v14
	v_fmac_f32_e32 v25, v26, v82
	v_fma_f32 v24, -v81, v25, v24
	v_div_fmas_f32 v15, v24, v82, v25
	v_lshl_add_u64 v[24:25], v[12:13], 1, v[4:5]
	v_mul_f32_e32 v13, 0x45800000, v14
	v_cndmask_b32_e64 v14, v14, v13, s[4:5]
	v_pk_mul_f32 v[26:27], v[42:43], v[14:15] op_sel_hi:[1,0]
	v_div_fixup_f32 v46, v15, v68, v80
	s_waitcnt vmcnt(0)
	v_pk_mul_f32 v[0:1], v[0:1], v[26:27]
	v_pk_mul_f32 v[26:27], v[40:41], v[14:15] op_sel_hi:[1,0]
	v_pk_mul_f32 v[0:1], v[70:71], v[0:1]
	v_pk_mul_f32 v[2:3], v[2:3], v[26:27]
	v_cvt_pk_bf16_f32 v0, v0, v1
	v_pk_mul_f32 v[2:3], v[46:47], v[2:3]
	v_or_b32_e32 v40, s8, v124
	v_cvt_pk_bf16_f32 v1, v2, v3
	global_store_dwordx2 v[24:25], v[0:1], off
	v_mov_b64_e32 v[2:3], v[154:155]
	v_lshl_add_u64 v[0:1], s[8:9], 0, v[208:209]
	v_lshl_add_u64 v[0:1], v[0:1], 2, s[76:77]
	v_mov_b64_e32 v[24:25], v[168:169]
	v_mov_b64_e32 v[26:27], v[170:171]
	v_ashrrev_i32_e32 v41, 31, v40
	v_lshl_add_u64 v[40:41], v[40:41], 1, v[4:5]
	s_mov_b32 s76, s43
	v_lshlrev_b32_e32 v13, 16, v2
	v_and_b32_e32 v15, 0xffff0000, v2
	v_mul_f32_e32 v2, 0xbfb8aa3b, v13
	v_exp_f32_e32 v42, v2
	v_mul_f32_e32 v2, 0xbfb8aa3b, v15
	v_exp_f32_e32 v43, v2
	v_lshlrev_b32_e32 v50, 16, v3
	v_and_b32_e32 v51, 0xffff0000, v3
	v_pk_mul_f32 v[2:3], v[48:49], v[14:15] op_sel_hi:[1,0]
	v_pk_add_f32 v[42:43], v[42:43], 1.0 op_sel_hi:[1,0]
	v_pk_mul_f32 v[2:3], v[24:25], v[2:3]
	v_div_scale_f32 v46, s[4:5], v43, v43, v15
	v_rcp_f32_e32 v47, v46
	s_nop 0
	v_fma_f32 v24, -v46, v47, 1.0
	v_fmac_f32_e32 v47, v24, v47
	v_div_scale_f32 v24, vcc, v15, v43, v15
	v_mul_f32_e32 v25, v24, v47
	v_fma_f32 v48, -v46, v25, v24
	v_fmac_f32_e32 v25, v48, v47
	v_fma_f32 v24, -v46, v25, v24
	v_div_scale_f32 v46, s[4:5], v42, v42, v13
	v_rcp_f32_e32 v48, v46
	v_div_fmas_f32 v24, v24, v47, v25
	v_div_fixup_f32 v25, v24, v43, v15
	v_fma_f32 v15, -v46, v48, 1.0
	v_fmac_f32_e32 v48, v15, v48
	v_div_scale_f32 v15, vcc, v13, v42, v13
	v_mul_f32_e32 v24, v15, v48
	v_fma_f32 v43, -v46, v24, v15
	v_fmac_f32_e32 v24, v43, v48
	v_mul_f32_e32 v43, 0xbfb8aa3b, v50
	v_fma_f32 v15, -v46, v24, v15
	v_exp_f32_e32 v46, v43
	v_mul_f32_e32 v43, 0xbfb8aa3b, v51
	v_exp_f32_e32 v47, v43
	v_div_fmas_f32 v15, v15, v48, v24
	v_div_fixup_f32 v24, v15, v42, v13
	v_pk_mul_f32 v[2:3], v[24:25], v[2:3]
	v_pk_add_f32 v[24:25], v[46:47], 1.0 op_sel_hi:[1,0]
	v_cvt_pk_bf16_f32 v2, v2, v3
	v_div_scale_f32 v13, s[4:5], v25, v25, v51
	v_rcp_f32_e32 v15, v13
	s_nop 0
	v_fma_f32 v3, -v13, v15, 1.0
	v_pk_mul_f32 v[42:43], v[44:45], v[14:15] op_sel_hi:[1,0]
	v_fmac_f32_e32 v15, v3, v15
	v_div_scale_f32 v3, vcc, v51, v25, v51
	v_pk_mul_f32 v[26:27], v[26:27], v[42:43]
	v_mul_f32_e32 v42, v3, v15
	v_fma_f32 v43, -v13, v42, v3
	v_fmac_f32_e32 v42, v43, v15
	v_fma_f32 v3, -v13, v42, v3
	v_div_scale_f32 v13, s[4:5], v24, v24, v50
	v_rcp_f32_e32 v43, v13
	v_div_fmas_f32 v3, v3, v15, v42
	v_div_fixup_f32 v25, v3, v25, v51
	v_fma_f32 v3, -v13, v43, 1.0
	v_fmac_f32_e32 v43, v3, v43
	v_div_scale_f32 v3, vcc, v50, v24, v50
	v_mul_f32_e32 v15, v3, v43
	v_fma_f32 v42, -v13, v15, v3
	v_fmac_f32_e32 v15, v42, v43
	v_fma_f32 v3, -v13, v15, v3
	v_div_fmas_f32 v3, v3, v43, v15
	v_div_fixup_f32 v24, v3, v24, v50
	v_pk_mul_f32 v[24:25], v[24:25], v[26:27]
	v_pk_mul_f32 v[38:39], v[38:39], v[14:15] op_sel_hi:[1,0]
	v_cvt_pk_bf16_f32 v3, v24, v25
	global_store_dwordx2 v[40:41], v[2:3], off
	v_mov_b64_e32 v[2:3], v[156:157]
	s_nop 0
	v_mov_b64_e32 v[24:25], v[172:173]
	v_mov_b64_e32 v[26:27], v[174:175]
	v_or_b32_e32 v40, s8, v123
	v_ashrrev_i32_e32 v41, 31, v40
	v_lshl_add_u64 v[40:41], v[40:41], 1, v[4:5]
	v_lshlrev_b32_e32 v13, 16, v2
	v_and_b32_e32 v15, 0xffff0000, v2
	v_lshlrev_b32_e32 v42, 16, v3
	v_and_b32_e32 v43, 0xffff0000, v3
	v_pk_mul_f32 v[2:3], v[24:25], v[38:39]
	v_mul_f32_e32 v24, 0xbfb8aa3b, v13
	v_mul_f32_e32 v25, 0xbfb8aa3b, v15
	v_exp_f32_e32 v24, v24
	v_exp_f32_e32 v25, v25
	v_mul_f32_e32 v38, 0xbfb8aa3b, v42
	v_mul_f32_e32 v39, 0xbfb8aa3b, v43
	v_exp_f32_e32 v38, v38
	v_pk_add_f32 v[24:25], v[24:25], 1.0 op_sel_hi:[1,0]
	v_exp_f32_e32 v39, v39
	v_div_scale_f32 v44, s[4:5], v25, v25, v15
	v_div_scale_f32 v46, s[4:5], v24, v24, v13
	v_rcp_f32_e32 v47, v44
	v_rcp_f32_e32 v48, v46
	v_div_scale_f32 v45, vcc, v15, v25, v15
	v_fma_f32 v50, -v44, v47, 1.0
	v_fma_f32 v51, -v46, v48, 1.0
	v_fmac_f32_e32 v47, v50, v47
	v_div_scale_f32 v49, s[4:5], v13, v24, v13
	v_fmac_f32_e32 v48, v51, v48
	v_mul_f32_e32 v50, v45, v47
	v_mul_f32_e32 v51, v49, v48
	v_fma_f32 v52, -v44, v50, v45
	v_fma_f32 v53, -v46, v51, v49
	v_fmac_f32_e32 v50, v52, v47
	v_fmac_f32_e32 v51, v53, v48
	v_fma_f32 v44, -v44, v50, v45
	v_fma_f32 v45, -v46, v51, v49
	v_div_fmas_f32 v44, v44, v47, v50
	s_mov_b64 vcc, s[4:5]
	v_div_fixup_f32 v25, v44, v25, v15
	v_div_fmas_f32 v15, v45, v48, v51
	v_div_fixup_f32 v24, v15, v24, v13
	v_pk_mul_f32 v[2:3], v[24:25], v[2:3]
	v_pk_add_f32 v[24:25], v[38:39], 1.0 op_sel_hi:[1,0]
	v_cvt_pk_bf16_f32 v2, v2, v3
	v_div_scale_f32 v13, s[4:5], v25, v25, v43
	v_rcp_f32_e32 v15, v13
	s_nop 0
	v_fma_f32 v3, -v13, v15, 1.0
	v_pk_mul_f32 v[34:35], v[34:35], v[14:15] op_sel_hi:[1,0]
	v_fmac_f32_e32 v15, v3, v15
	v_div_scale_f32 v3, vcc, v43, v25, v43
	v_pk_mul_f32 v[26:27], v[26:27], v[34:35]
	v_mul_f32_e32 v34, v3, v15
	v_fma_f32 v35, -v13, v34, v3
	v_fmac_f32_e32 v34, v35, v15
	v_fma_f32 v3, -v13, v34, v3
	v_div_scale_f32 v13, s[4:5], v24, v24, v42
	v_rcp_f32_e32 v35, v13
	v_div_fmas_f32 v3, v3, v15, v34
	v_div_fixup_f32 v25, v3, v25, v43
	v_fma_f32 v3, -v13, v35, 1.0
	v_fmac_f32_e32 v35, v3, v35
	v_div_scale_f32 v3, vcc, v42, v24, v42
	v_mul_f32_e32 v15, v3, v35
	v_fma_f32 v34, -v13, v15, v3
	v_fmac_f32_e32 v15, v34, v35
	v_fma_f32 v3, -v13, v15, v3
	v_div_fmas_f32 v3, v3, v35, v15
	v_div_fixup_f32 v24, v3, v24, v42
	v_pk_mul_f32 v[24:25], v[24:25], v[26:27]
	v_pk_mul_f32 v[36:37], v[36:37], v[14:15] op_sel_hi:[1,0]
	v_cvt_pk_bf16_f32 v3, v24, v25
	global_store_dwordx2 v[40:41], v[2:3], off
	v_mov_b64_e32 v[2:3], v[158:159]
	s_nop 0
	v_mov_b64_e32 v[24:25], v[176:177]
	v_mov_b64_e32 v[26:27], v[178:179]
	v_pk_mul_f32 v[32:33], v[32:33], v[14:15] op_sel_hi:[1,0]
	v_or_b32_e32 v34, s8, v122
	v_ashrrev_i32_e32 v35, 31, v34
	v_lshl_add_u64 v[34:35], v[34:35], 1, v[4:5]
	v_lshlrev_b32_e32 v13, 16, v2
	v_and_b32_e32 v15, 0xffff0000, v2
	v_lshlrev_b32_e32 v40, 16, v3
	v_and_b32_e32 v41, 0xffff0000, v3
	v_mul_f32_e32 v2, 0xbfb8aa3b, v13
	v_mul_f32_e32 v3, 0xbfb8aa3b, v15
	v_exp_f32_e32 v2, v2
	v_exp_f32_e32 v3, v3
	v_mul_f32_e32 v38, 0xbfb8aa3b, v40
	v_mul_f32_e32 v39, 0xbfb8aa3b, v41
	v_exp_f32_e32 v38, v38
	v_exp_f32_e32 v39, v39
	v_pk_add_f32 v[2:3], v[2:3], 1.0 op_sel_hi:[1,0]
	v_pk_mul_f32 v[24:25], v[24:25], v[36:37]
	v_div_scale_f32 v36, s[4:5], v3, v3, v15
	v_pk_mul_f32 v[26:27], v[26:27], v[32:33]
	v_pk_add_f32 v[32:33], v[38:39], 1.0 op_sel_hi:[1,0]
	v_div_scale_f32 v38, s[4:5], v2, v2, v13
	v_rcp_f32_e32 v45, v36
	v_rcp_f32_e32 v46, v38
	v_div_scale_f32 v42, s[6:7], v33, v33, v41
	v_rcp_f32_e32 v47, v42
	v_fma_f32 v49, -v36, v45, 1.0
	v_div_scale_f32 v37, vcc, v15, v3, v15
	v_fma_f32 v50, -v38, v46, 1.0
	v_fmac_f32_e32 v45, v49, v45
	v_div_scale_f32 v39, s[4:5], v13, v2, v13
	v_fmac_f32_e32 v46, v50, v46
	v_mul_f32_e32 v49, v37, v45
	v_mul_f32_e32 v50, v39, v46
	v_fma_f32 v53, -v36, v49, v37
	v_div_scale_f32 v44, s[8:9], v32, v32, v40
	v_fma_f32 v51, -v42, v47, 1.0
	v_fma_f32 v54, -v38, v50, v39
	v_fmac_f32_e32 v49, v53, v45
	v_div_scale_f32 v43, s[6:7], v41, v33, v41
	v_rcp_f32_e32 v48, v44
	v_fmac_f32_e32 v47, v51, v47
	v_fmac_f32_e32 v50, v54, v46
	v_fma_f32 v36, -v36, v49, v37
	v_mul_f32_e32 v51, v43, v47
	v_fma_f32 v37, -v38, v50, v39
	v_div_fmas_f32 v36, v36, v45, v49
	s_mov_b64 vcc, s[4:5]
	v_fma_f32 v55, -v42, v51, v43
	v_div_fixup_f32 v3, v36, v3, v15
	v_div_fmas_f32 v15, v37, v46, v50
	v_fmac_f32_e32 v51, v55, v47
	v_div_fixup_f32 v2, v15, v2, v13
	v_fma_f32 v52, -v44, v48, 1.0
	v_fma_f32 v38, -v42, v51, v43
	s_mov_b64 vcc, s[6:7]
	v_pk_mul_f32 v[2:3], v[2:3], v[24:25]
	v_div_fmas_f32 v13, v38, v47, v51
	v_cvt_pk_bf16_f32 v2, v2, v3
	v_fmac_f32_e32 v48, v52, v48
	v_div_scale_f32 v3, vcc, v40, v32, v40
	v_div_fixup_f32 v25, v13, v33, v41
	v_mul_f32_e32 v13, v3, v48
	v_fma_f32 v15, -v44, v13, v3
	v_fmac_f32_e32 v13, v15, v48
	v_fma_f32 v3, -v44, v13, v3
	v_div_fmas_f32 v3, v3, v48, v13
	v_div_fixup_f32 v24, v3, v32, v40
	v_pk_mul_f32 v[24:25], v[24:25], v[26:27]
	v_pk_mul_f32 v[28:29], v[28:29], v[14:15] op_sel_hi:[1,0]
	v_cvt_pk_bf16_f32 v3, v24, v25
	global_store_dwordx2 v[34:35], v[2:3], off
	v_mov_b64_e32 v[2:3], v[160:161]
	s_nop 0
	v_mov_b64_e32 v[24:25], v[180:181]
	v_mov_b64_e32 v[26:27], v[182:183]
	v_pk_mul_f32 v[30:31], v[30:31], v[14:15] op_sel_hi:[1,0]
	v_or_b32_e32 v32, 64, v12
	v_ashrrev_i32_e32 v33, 31, v32
	v_lshl_add_u64 v[32:33], v[32:33], 1, v[4:5]
	v_lshlrev_b32_e32 v13, 16, v2
	v_and_b32_e32 v15, 0xffff0000, v2
	v_lshlrev_b32_e32 v36, 16, v3
	v_and_b32_e32 v37, 0xffff0000, v3
	v_mul_f32_e32 v2, 0xbfb8aa3b, v13
	v_mul_f32_e32 v3, 0xbfb8aa3b, v15
	v_exp_f32_e32 v2, v2
	v_exp_f32_e32 v3, v3
	v_mul_f32_e32 v34, 0xbfb8aa3b, v36
	v_mul_f32_e32 v35, 0xbfb8aa3b, v37
	v_exp_f32_e32 v34, v34
	v_exp_f32_e32 v35, v35
	v_pk_add_f32 v[2:3], v[2:3], 1.0 op_sel_hi:[1,0]
	v_pk_mul_f32 v[26:27], v[26:27], v[30:31]
	v_div_scale_f32 v30, s[4:5], v3, v3, v15
	v_pk_mul_f32 v[24:25], v[24:25], v[28:29]
	v_pk_add_f32 v[28:29], v[34:35], 1.0 op_sel_hi:[1,0]
	v_div_scale_f32 v34, s[4:5], v2, v2, v13
	v_rcp_f32_e32 v42, v30
	v_div_scale_f32 v38, s[6:7], v29, v29, v37
	v_rcp_f32_e32 v43, v34
	v_div_scale_f32 v40, s[8:9], v28, v28, v36
	v_rcp_f32_e32 v44, v38
	v_rcp_f32_e32 v45, v40
	v_fma_f32 v46, -v30, v42, 1.0
	v_div_scale_f32 v31, vcc, v15, v3, v15
	v_fma_f32 v47, -v34, v43, 1.0
	v_fmac_f32_e32 v42, v46, v42
	v_div_scale_f32 v35, s[4:5], v13, v2, v13
	v_fma_f32 v48, -v38, v44, 1.0
	v_fmac_f32_e32 v43, v47, v43
	v_mul_f32_e32 v46, v31, v42
	v_div_scale_f32 v39, s[6:7], v37, v29, v37
	v_fma_f32 v49, -v40, v45, 1.0
	v_fmac_f32_e32 v44, v48, v44
	v_mul_f32_e32 v47, v35, v43
	v_fma_f32 v50, -v30, v46, v31
	v_div_scale_f32 v41, s[8:9], v36, v28, v36
	v_fmac_f32_e32 v45, v49, v45
	v_mul_f32_e32 v48, v39, v44
	v_fma_f32 v51, -v34, v47, v35
	v_fmac_f32_e32 v46, v50, v42
	v_mul_f32_e32 v49, v41, v45
	v_fma_f32 v52, -v38, v48, v39
	v_fmac_f32_e32 v47, v51, v43
	v_fma_f32 v30, -v30, v46, v31
	v_fma_f32 v53, -v40, v49, v41
	v_fmac_f32_e32 v48, v52, v44
	v_fma_f32 v31, -v34, v47, v35
	v_div_fmas_f32 v30, v30, v42, v46
	s_mov_b64 vcc, s[4:5]
	v_fmac_f32_e32 v49, v53, v45
	v_fma_f32 v34, -v38, v48, v39
	v_div_fixup_f32 v3, v30, v3, v15
	v_div_fmas_f32 v15, v31, v43, v47
	s_mov_b64 vcc, s[6:7]
	v_fma_f32 v35, -v40, v49, v41
	v_div_fixup_f32 v2, v15, v2, v13
	v_div_fmas_f32 v13, v34, v44, v48
	s_mov_b64 vcc, s[8:9]
	v_pk_mul_f32 v[2:3], v[2:3], v[24:25]
	v_div_fixup_f32 v25, v13, v29, v37
	v_div_fmas_f32 v13, v35, v45, v49
	v_div_fixup_f32 v24, v13, v28, v36
	v_pk_mul_f32 v[24:25], v[24:25], v[26:27]
	v_cvt_pk_bf16_f32 v2, v2, v3
	v_cvt_pk_bf16_f32 v3, v24, v25
	global_store_dwordx2 v[32:33], v[2:3], off
	v_mov_b64_e32 v[2:3], v[162:163]
	s_nop 0
	v_mov_b64_e32 v[24:25], v[184:185]
	v_mov_b64_e32 v[26:27], v[186:187]
	v_pk_mul_f32 v[20:21], v[20:21], v[14:15] op_sel_hi:[1,0]
	v_pk_mul_f32 v[22:23], v[22:23], v[14:15] op_sel_hi:[1,0]
	v_or_b32_e32 v28, 0x50, v12
	v_ashrrev_i32_e32 v29, 31, v28
	v_lshl_add_u64 v[28:29], v[28:29], 1, v[4:5]
	v_lshlrev_b32_e32 v13, 16, v2
	v_and_b32_e32 v15, 0xffff0000, v2
	v_lshlrev_b32_e32 v32, 16, v3
	v_and_b32_e32 v33, 0xffff0000, v3
	v_mul_f32_e32 v2, 0xbfb8aa3b, v13
	v_mul_f32_e32 v3, 0xbfb8aa3b, v15
	v_exp_f32_e32 v2, v2
	v_exp_f32_e32 v3, v3
	v_mul_f32_e32 v30, 0xbfb8aa3b, v32
	v_mul_f32_e32 v31, 0xbfb8aa3b, v33
	v_exp_f32_e32 v30, v30
	v_exp_f32_e32 v31, v31
	v_pk_add_f32 v[2:3], v[2:3], 1.0 op_sel_hi:[1,0]
	v_pk_mul_f32 v[22:23], v[26:27], v[22:23]
	v_div_scale_f32 v26, s[4:5], v3, v3, v15
	v_pk_mul_f32 v[20:21], v[24:25], v[20:21]
	v_pk_add_f32 v[24:25], v[30:31], 1.0 op_sel_hi:[1,0]
	v_div_scale_f32 v30, s[4:5], v2, v2, v13
	v_rcp_f32_e32 v38, v26
	v_div_scale_f32 v34, s[6:7], v25, v25, v33
	v_rcp_f32_e32 v39, v30
	v_div_scale_f32 v36, s[8:9], v24, v24, v32
	v_rcp_f32_e32 v40, v34
	v_rcp_f32_e32 v41, v36
	v_fma_f32 v42, -v26, v38, 1.0
	v_div_scale_f32 v27, vcc, v15, v3, v15
	v_fma_f32 v43, -v30, v39, 1.0
	v_fmac_f32_e32 v38, v42, v38
	v_div_scale_f32 v31, s[4:5], v13, v2, v13
	v_fma_f32 v44, -v34, v40, 1.0
	v_fmac_f32_e32 v39, v43, v39
	v_mul_f32_e32 v42, v27, v38
	v_div_scale_f32 v35, s[6:7], v33, v25, v33
	v_fma_f32 v45, -v36, v41, 1.0
	v_fmac_f32_e32 v40, v44, v40
	v_mul_f32_e32 v43, v31, v39
	v_fma_f32 v46, -v26, v42, v27
	v_div_scale_f32 v37, s[8:9], v32, v24, v32
	v_fmac_f32_e32 v41, v45, v41
	v_mul_f32_e32 v44, v35, v40
	v_fma_f32 v47, -v30, v43, v31
	v_fmac_f32_e32 v42, v46, v38
	v_mul_f32_e32 v45, v37, v41
	v_fma_f32 v48, -v34, v44, v35
	v_fmac_f32_e32 v43, v47, v39
	v_fma_f32 v26, -v26, v42, v27
	v_fma_f32 v49, -v36, v45, v37
	v_fmac_f32_e32 v44, v48, v40
	v_fma_f32 v27, -v30, v43, v31
	v_div_fmas_f32 v26, v26, v38, v42
	s_mov_b64 vcc, s[4:5]
	v_fmac_f32_e32 v45, v49, v41
	v_fma_f32 v30, -v34, v44, v35
	v_div_fixup_f32 v3, v26, v3, v15
	v_div_fmas_f32 v15, v27, v39, v43
	s_mov_b64 vcc, s[6:7]
	v_fma_f32 v31, -v36, v45, v37
	v_div_fixup_f32 v2, v15, v2, v13
	v_div_fmas_f32 v13, v30, v40, v44
	s_mov_b64 vcc, s[8:9]
	v_pk_mul_f32 v[2:3], v[2:3], v[20:21]
	v_div_fixup_f32 v21, v13, v25, v33
	v_div_fmas_f32 v13, v31, v41, v45
	v_div_fixup_f32 v20, v13, v24, v32
	v_pk_mul_f32 v[20:21], v[20:21], v[22:23]
	v_cvt_pk_bf16_f32 v2, v2, v3
	v_cvt_pk_bf16_f32 v3, v20, v21
	global_store_dwordx2 v[28:29], v[2:3], off
	v_mov_b64_e32 v[2:3], v[164:165]
	s_nop 0
	v_mov_b64_e32 v[20:21], v[188:189]
	v_mov_b64_e32 v[22:23], v[190:191]
	v_pk_mul_f32 v[18:19], v[18:19], v[14:15] op_sel_hi:[1,0]
	v_pk_mul_f32 v[16:17], v[16:17], v[14:15] op_sel_hi:[1,0]
	v_or_b32_e32 v24, 0x60, v12
	v_ashrrev_i32_e32 v25, 31, v24
	v_lshl_add_u64 v[24:25], v[24:25], 1, v[4:5]
	v_or_b32_e32 v12, 0x70, v12
	v_lshlrev_b32_e32 v13, 16, v2
	v_and_b32_e32 v15, 0xffff0000, v2
	v_lshlrev_b32_e32 v28, 16, v3
	v_and_b32_e32 v29, 0xffff0000, v3
	v_mul_f32_e32 v2, 0xbfb8aa3b, v13
	v_mul_f32_e32 v3, 0xbfb8aa3b, v15
	v_exp_f32_e32 v2, v2
	v_exp_f32_e32 v3, v3
	v_mul_f32_e32 v26, 0xbfb8aa3b, v28
	v_mul_f32_e32 v27, 0xbfb8aa3b, v29
	v_exp_f32_e32 v26, v26
	v_exp_f32_e32 v27, v27
	v_pk_add_f32 v[2:3], v[2:3], 1.0 op_sel_hi:[1,0]
	v_pk_mul_f32 v[16:17], v[22:23], v[16:17]
	v_div_scale_f32 v22, s[4:5], v3, v3, v15
	v_pk_mul_f32 v[18:19], v[20:21], v[18:19]
	v_pk_add_f32 v[20:21], v[26:27], 1.0 op_sel_hi:[1,0]
	v_div_scale_f32 v26, s[4:5], v2, v2, v13
	v_rcp_f32_e32 v34, v22
	v_div_scale_f32 v30, s[6:7], v21, v21, v29
	v_rcp_f32_e32 v35, v26
	v_div_scale_f32 v32, s[8:9], v20, v20, v28
	v_rcp_f32_e32 v36, v30
	v_rcp_f32_e32 v37, v32
	v_fma_f32 v38, -v22, v34, 1.0
	v_div_scale_f32 v23, vcc, v15, v3, v15
	v_fma_f32 v39, -v26, v35, 1.0
	v_fmac_f32_e32 v34, v38, v34
	v_div_scale_f32 v27, s[4:5], v13, v2, v13
	v_fma_f32 v40, -v30, v36, 1.0
	v_fmac_f32_e32 v35, v39, v35
	v_mul_f32_e32 v38, v23, v34
	v_div_scale_f32 v31, s[6:7], v29, v21, v29
	v_fma_f32 v41, -v32, v37, 1.0
	v_fmac_f32_e32 v36, v40, v36
	v_mul_f32_e32 v39, v27, v35
	v_fma_f32 v42, -v22, v38, v23
	v_div_scale_f32 v33, s[8:9], v28, v20, v28
	v_fmac_f32_e32 v37, v41, v37
	v_mul_f32_e32 v40, v31, v36
	v_fma_f32 v43, -v26, v39, v27
	v_fmac_f32_e32 v38, v42, v34
	v_mul_f32_e32 v41, v33, v37
	v_fma_f32 v44, -v30, v40, v31
	v_fmac_f32_e32 v39, v43, v35
	v_fma_f32 v22, -v22, v38, v23
	v_fma_f32 v45, -v32, v41, v33
	v_fmac_f32_e32 v40, v44, v36
	v_fma_f32 v23, -v26, v39, v27
	v_div_fmas_f32 v22, v22, v34, v38
	s_mov_b64 vcc, s[4:5]
	v_fmac_f32_e32 v41, v45, v37
	v_fma_f32 v26, -v30, v40, v31
	v_div_fixup_f32 v3, v22, v3, v15
	v_div_fmas_f32 v15, v23, v35, v39
	s_mov_b64 vcc, s[6:7]
	v_fma_f32 v27, -v32, v41, v33
	v_div_fixup_f32 v2, v15, v2, v13
	v_div_fmas_f32 v13, v26, v36, v40
	s_mov_b64 vcc, s[8:9]
	v_pk_mul_f32 v[2:3], v[2:3], v[18:19]
	v_div_fixup_f32 v19, v13, v21, v29
	v_div_fmas_f32 v13, v27, v37, v41
	v_div_fixup_f32 v18, v13, v20, v28
	v_pk_mul_f32 v[16:17], v[18:19], v[16:17]
	v_cvt_pk_bf16_f32 v2, v2, v3
	v_cvt_pk_bf16_f32 v3, v16, v17
	global_store_dwordx2 v[24:25], v[2:3], off
	v_mov_b64_e32 v[10:11], v[166:167]
	s_nop 0
	v_mov_b64_e32 v[0:1], v[192:193]
	v_mov_b64_e32 v[2:3], v[194:195]
	v_pk_mul_f32 v[6:7], v[6:7], v[14:15] op_sel_hi:[1,0]
	v_pk_mul_f32 v[8:9], v[8:9], v[14:15] op_sel_hi:[1,0]
	v_ashrrev_i32_e32 v13, 31, v12
	v_lshl_add_u64 v[4:5], v[12:13], 1, v[4:5]
	v_lshlrev_b32_e32 v14, 16, v10
	v_and_b32_e32 v15, 0xffff0000, v10
	v_lshlrev_b32_e32 v16, 16, v11
	v_and_b32_e32 v17, 0xffff0000, v11
	v_mul_f32_e32 v10, 0xbfb8aa3b, v14
	v_mul_f32_e32 v11, 0xbfb8aa3b, v15
	v_exp_f32_e32 v10, v10
	v_exp_f32_e32 v11, v11
	v_mul_f32_e32 v12, 0xbfb8aa3b, v16
	v_mul_f32_e32 v13, 0xbfb8aa3b, v17
	v_exp_f32_e32 v12, v12
	v_exp_f32_e32 v13, v13
	v_pk_mul_f32 v[0:1], v[0:1], v[6:7]
	v_pk_add_f32 v[6:7], v[10:11], 1.0 op_sel_hi:[1,0]
	v_pk_mul_f32 v[2:3], v[2:3], v[8:9]
	v_div_scale_f32 v10, s[4:5], v7, v7, v15
	v_pk_add_f32 v[8:9], v[12:13], 1.0 op_sel_hi:[1,0]
	v_div_scale_f32 v12, s[4:5], v6, v6, v14
	v_rcp_f32_e32 v22, v10
	v_div_scale_f32 v18, s[6:7], v9, v9, v17
	v_rcp_f32_e32 v23, v12
	v_div_scale_f32 v20, s[8:9], v8, v8, v16
	v_rcp_f32_e32 v24, v18
	v_rcp_f32_e32 v25, v20
	v_fma_f32 v26, -v10, v22, 1.0
	v_div_scale_f32 v11, vcc, v15, v7, v15
	v_fma_f32 v27, -v12, v23, 1.0
	v_fmac_f32_e32 v22, v26, v22
	v_div_scale_f32 v13, s[4:5], v14, v6, v14
	v_fma_f32 v28, -v18, v24, 1.0
	v_fmac_f32_e32 v23, v27, v23
	v_mul_f32_e32 v26, v11, v22
	v_div_scale_f32 v19, s[6:7], v17, v9, v17
	v_fma_f32 v29, -v20, v25, 1.0
	v_fmac_f32_e32 v24, v28, v24
	v_mul_f32_e32 v27, v13, v23
	v_fma_f32 v30, -v10, v26, v11
	v_div_scale_f32 v21, s[8:9], v16, v8, v16
	v_fmac_f32_e32 v25, v29, v25
	v_mul_f32_e32 v28, v19, v24
	v_fma_f32 v31, -v12, v27, v13
	v_fmac_f32_e32 v26, v30, v22
	v_mul_f32_e32 v29, v21, v25
	v_fma_f32 v32, -v18, v28, v19
	v_fmac_f32_e32 v27, v31, v23
	v_fma_f32 v10, -v10, v26, v11
	v_fma_f32 v33, -v20, v29, v21
	v_fmac_f32_e32 v28, v32, v24
	v_fma_f32 v11, -v12, v27, v13
	v_div_fmas_f32 v10, v10, v22, v26
	s_mov_b64 vcc, s[4:5]
	v_fmac_f32_e32 v29, v33, v25
	v_fma_f32 v12, -v18, v28, v19
	v_div_fixup_f32 v7, v10, v7, v15
	v_div_fmas_f32 v10, v11, v23, v27
	s_mov_b64 vcc, s[6:7]
	v_fma_f32 v13, -v20, v29, v21
	v_div_fixup_f32 v6, v10, v6, v14
	v_div_fmas_f32 v10, v12, v24, v28
	s_mov_b64 vcc, s[8:9]
	v_pk_mul_f32 v[0:1], v[6:7], v[0:1]
	v_div_fmas_f32 v6, v13, v25, v29
	v_div_fixup_f32 v7, v10, v9, v17
	v_div_fixup_f32 v6, v6, v8, v16
	v_pk_mul_f32 v[2:3], v[6:7], v[2:3]
	v_cvt_pk_bf16_f32 v0, v0, v1
	v_cvt_pk_bf16_f32 v1, v2, v3
	s_mov_b64 s[4:5], 0
	global_store_dwordx2 v[4:5], v[0:1], off

.LBB0_1124:
	v_max_f32_e32 v81, v137, v137
	v_mov_b32_e32 v80, v81
	s_nop 1
	v_permlane16_swap_b32_e32 v80, v81
	v_max_f32_e32 v80, v80, v81
	v_mov_b32_e32 v81, v80
	s_nop 1
	v_permlane32_swap_b32_e32 v80, v81
	v_max3_f32 v88, v136, v80, v81
	v_sub_f32_e32 v80, v136, v88
	v_exp_f32_e32 v90, v80
	v_sub_f32_e32 v80, v120, v88
	v_exp_f32_e32 v80, v80
	v_sub_f32_e32 v82, v121, v88
	v_exp_f32_e32 v82, v82
	v_sub_f32_e32 v83, v112, v88
	v_exp_f32_e32 v83, v83
	v_sub_f32_e32 v84, v113, v88
	v_exp_f32_e32 v84, v84
	v_sub_f32_e32 v85, v108, v88
	v_fma_f32 v81, v135, v90, v80
	v_exp_f32_e32 v85, v85
	v_sub_f32_e32 v86, v109, v88
	v_add_f32_e32 v81, v82, v81
	v_exp_f32_e32 v86, v86
	v_sub_f32_e32 v87, v106, v88
	v_add_f32_e32 v81, v83, v81
	v_exp_f32_e32 v87, v87
	v_sub_f32_e32 v89, v107, v88
	v_add_f32_e32 v81, v84, v81
	v_exp_f32_e32 v89, v89
	v_add_f32_e32 v81, v85, v81
	v_add_f32_e32 v81, v86, v81
	v_add_f32_e32 v81, v87, v81
	v_add_f32_e32 v91, v89, v81
	v_cvt_pk_bf16_f32 v81, v83, v84
	v_sub_f32_e32 v84, v110, v88
	v_cvt_pk_bf16_f32 v83, v87, v89
	v_exp_f32_e32 v89, v84
	v_sub_f32_e32 v84, v111, v88
	v_exp_f32_e32 v92, v84
	v_sub_f32_e32 v84, v114, v88
	v_exp_f32_e32 v93, v84
	v_sub_f32_e32 v84, v115, v88
	v_exp_f32_e32 v94, v84
	v_sub_f32_e32 v84, v116, v88
	v_exp_f32_e32 v95, v84
	v_sub_f32_e32 v84, v117, v88
	v_exp_f32_e32 v106, v84
	v_sub_f32_e32 v84, v118, v88
	v_exp_f32_e32 v107, v84
	v_sub_f32_e32 v84, v119, v88
	v_exp_f32_e32 v135, v84
	v_cvt_pk_bf16_f32 v84, v89, v92
	v_add_f32_e32 v89, v89, v91
	v_add_f32_e32 v89, v92, v89
	v_add_f32_e32 v89, v93, v89
	v_add_f32_e32 v89, v94, v89
	v_add_f32_e32 v89, v95, v89
	v_cvt_pk_bf16_f32 v80, v80, v82
	v_cvt_pk_bf16_f32 v82, v85, v86
	v_cvt_pk_bf16_f32 v85, v93, v94
	v_add_f32_e32 v89, v106, v89
	v_cvt_pk_bf16_f32 v86, v95, v106
	v_cvt_pk_bf16_f32 v87, v107, v135
	v_pk_mul_f32 v[74:75], v[74:75], v[90:91] op_sel_hi:[1,0]
	v_pk_mul_f32 v[72:73], v[72:73], v[90:91] op_sel_hi:[1,0]
	v_pk_mul_f32 v[70:71], v[70:71], v[90:91] op_sel_hi:[1,0]
	v_pk_mul_f32 v[68:69], v[68:69], v[90:91] op_sel_hi:[1,0]
	v_pk_mul_f32 v[58:59], v[58:59], v[90:91] op_sel_hi:[1,0]
	v_pk_mul_f32 v[56:57], v[56:57], v[90:91] op_sel_hi:[1,0]
	v_pk_mul_f32 v[18:19], v[18:19], v[90:91] op_sel_hi:[1,0]
	v_pk_mul_f32 v[16:17], v[16:17], v[90:91] op_sel_hi:[1,0]
	v_pk_mul_f32 v[30:31], v[30:31], v[90:91] op_sel_hi:[1,0]
	v_pk_mul_f32 v[28:29], v[28:29], v[90:91] op_sel_hi:[1,0]
	v_pk_mul_f32 v[22:23], v[22:23], v[90:91] op_sel_hi:[1,0]
	v_pk_mul_f32 v[20:21], v[20:21], v[90:91] op_sel_hi:[1,0]
	v_pk_mul_f32 v[26:27], v[26:27], v[90:91] op_sel_hi:[1,0]
	v_pk_mul_f32 v[24:25], v[24:25], v[90:91] op_sel_hi:[1,0]
	v_pk_mul_f32 v[78:79], v[78:79], v[90:91] op_sel_hi:[1,0]
	v_pk_mul_f32 v[76:77], v[76:77], v[90:91] op_sel_hi:[1,0]
	v_add_f32_e32 v89, v107, v89
	ds_read_b128 v[90:93], v134 offset:34816
	ds_read_b128 v[106:109], v134 offset:34880
	ds_read_b128 v[110:113], v134 offset:37120
	ds_read_b128 v[114:117], v134 offset:37184
	ds_read_b128 v[118:121], v134 offset:39424
	ds_read_b128 v[136:139], v134 offset:39488
	ds_read_b128 v[140:143], v134 offset:41728
	ds_read_b128 v[144:147], v134 offset:41792
	s_waitcnt lgkmcnt(7)
	v_mfma_f32_16x16x32_bf16 v[72:75], v[90:93], v[80:83], v[72:75]
	s_waitcnt lgkmcnt(5)
	v_mfma_f32_16x16x32_bf16 v[68:71], v[110:113], v[80:83], v[68:71]
	s_waitcnt lgkmcnt(3)
	v_mfma_f32_16x16x32_bf16 v[56:59], v[118:121], v[80:83], v[56:59]
	s_waitcnt lgkmcnt(1)
	v_mfma_f32_16x16x32_bf16 v[16:19], v[140:143], v[80:83], v[16:19]
	v_mfma_f32_16x16x32_bf16 v[72:75], v[106:109], v[84:87], v[72:75]
	v_mfma_f32_16x16x32_bf16 v[68:71], v[114:117], v[84:87], v[68:71]
	v_mfma_f32_16x16x32_bf16 v[56:59], v[136:139], v[84:87], v[56:59]
	s_waitcnt lgkmcnt(0)
	v_mfma_f32_16x16x32_bf16 v[16:19], v[144:147], v[84:87], v[16:19]
	ds_read_b128 v[90:93], v134 offset:44032
	ds_read_b128 v[106:109], v134 offset:44096
	ds_read_b128 v[110:113], v134 offset:46336
	ds_read_b128 v[114:117], v134 offset:46400
	ds_read_b128 v[118:121], v134 offset:48640
	ds_read_b128 v[136:139], v134 offset:48704
	ds_read_b128 v[140:143], v134 offset:50944
	ds_read_b128 v[144:147], v134 offset:51008
	s_waitcnt lgkmcnt(7)
	v_mfma_f32_16x16x32_bf16 v[28:31], v[90:93], v[80:83], v[28:31]
	s_waitcnt lgkmcnt(5)
	v_mfma_f32_16x16x32_bf16 v[20:23], v[110:113], v[80:83], v[20:23]
	s_waitcnt lgkmcnt(3)
	v_mfma_f32_16x16x32_bf16 v[24:27], v[118:121], v[80:83], v[24:27]
	s_waitcnt lgkmcnt(1)
	v_mfma_f32_16x16x32_bf16 v[76:79], v[140:143], v[80:83], v[76:79]
	v_mfma_f32_16x16x32_bf16 v[28:31], v[106:109], v[84:87], v[28:31]
	v_mfma_f32_16x16x32_bf16 v[20:23], v[114:117], v[84:87], v[20:23]
	v_mfma_f32_16x16x32_bf16 v[24:27], v[136:139], v[84:87], v[24:27]
	s_waitcnt lgkmcnt(0)
	v_mfma_f32_16x16x32_bf16 v[76:79], v[144:147], v[84:87], v[76:79]
	v_add_f32_e32 v135, v135, v89
	s_andn2_b64 vcc, exec, s[76:77]
	s_add_i32 s42, s42, 1
	s_cbranch_vccz .LBB0_1100
	v_mov_b32_e32 v136, v88
	v_add_u32_e32 v131, s32, v131
	v_add_u32_e32 v132, s32, v132
	v_add_u32_e32 v148, s32, v148
	v_add_u32_e32 v133, s32, v133
	v_add_u32_e32 v134, s32, v134
	s_sub_i32 s32, 0, s32
	s_branch .LBB0_1110

.LBB0_1269:
	v_readlane_b32 s86, v255, 6
	v_readlane_b32 s87, v255, 7
	v_readlane_b32 s80, v255, 0
	s_lshl_b64 s[4:5], s[86:87], 13
	v_readlane_b32 s82, v255, 2
	v_readlane_b32 s83, v255, 3
	s_add_u32 s4, s82, s4
	s_addc_u32 s5, s83, s5
	s_lshl_b32 s6, s46, 5
	s_lshl_b32 s7, s84, 8
	s_or_b32 s6, s7, s6
	v_lshl_or_b32 v212, v215, 2, s6
	v_ashrrev_i32_e32 v213, 31, v212
	v_lshlrev_b64 v[144:145], 2, v[212:213]
	s_lshl_b32 s13, s26, 8
	v_lshl_add_u64 v[128:129], s[4:5], 0, v[144:145]
	s_add_i32 s4, s13, s47
	v_or_b32_e32 v146, s4, v214
	v_readlane_b32 s4, v254, 60
	v_readlane_b32 s5, v254, 61
	v_ashrrev_i32_e32 v147, 31, v146
	s_waitcnt vmcnt(0)
	s_barrier
	v_lshl_add_u64 v[216:217], s[4:5], 0, v[144:145]
	v_lshlrev_b64 v[144:145], 13, v[146:147]
	v_lshl_add_u64 v[144:145], v[216:217], 0, v[144:145]
	global_load_dwordx4 v[140:143], v[128:129], off
	global_load_dwordx4 v[136:139], v[128:129], off offset:64
	global_load_dwordx4 v[132:135], v[128:129], off offset:512
	s_nop 0
	global_load_dwordx4 v[128:131], v[128:129], off offset:576
	s_nop 0
	global_load_dwordx4 v[204:207], v[144:145], off
	global_load_dwordx4 v[200:203], v[144:145], off offset:64
	global_load_dwordx4 v[196:199], v[144:145], off offset:512
	global_load_dwordx4 v[192:195], v[144:145], off offset:576
	v_or_b32_e32 v144, 16, v146
	v_ashrrev_i32_e32 v145, 31, v144
	v_lshlrev_b64 v[144:145], 13, v[144:145]
	v_lshl_add_u64 v[144:145], v[216:217], 0, v[144:145]
	global_load_dwordx4 v[188:191], v[144:145], off
	global_load_dwordx4 v[184:187], v[144:145], off offset:64
	global_load_dwordx4 v[180:183], v[144:145], off offset:512
	global_load_dwordx4 v[176:179], v[144:145], off offset:576
	v_or_b32_e32 v144, 32, v146
	v_ashrrev_i32_e32 v145, 31, v144
	v_lshlrev_b64 v[144:145], 13, v[144:145]
	v_lshl_add_u64 v[144:145], v[216:217], 0, v[144:145]
	global_load_dwordx4 v[172:175], v[144:145], off
	global_load_dwordx4 v[168:171], v[144:145], off offset:64
	global_load_dwordx4 v[164:167], v[144:145], off offset:512
	global_load_dwordx4 v[160:163], v[144:145], off offset:576
	v_or_b32_e32 v144, 48, v146
	v_ashrrev_i32_e32 v145, 31, v144
	v_lshlrev_b64 v[144:145], 13, v[144:145]
	v_lshl_add_u64 v[144:145], v[216:217], 0, v[144:145]
	global_load_dwordx4 v[156:159], v[144:145], off
	global_load_dwordx4 v[152:155], v[144:145], off offset:64
	global_load_dwordx4 v[148:151], v[144:145], off offset:512
	s_nop 0
	global_load_dwordx4 v[144:147], v[144:145], off offset:576
	v_and_b32_e32 v218, 64, v233
	v_xor_b32_e32 v208, 16, v233
	v_add_u32_e32 v218, 64, v218
	v_cmp_lt_i32_e32 vcc, v208, v218
	v_cmp_eq_u32_e64 s[4:5], 0, v215
	v_mul_f32_e32 v215, v125, v125
	v_cndmask_b32_e32 v208, v233, v208, vcc
	v_lshlrev_b32_e32 v248, 2, v208
	v_xor_b32_e32 v208, 32, v233
	v_cmp_lt_i32_e32 vcc, v208, v218
	v_mul_f32_e32 v218, v127, v127
	v_fmac_f32_e32 v215, v124, v124
	v_fmac_f32_e32 v218, v126, v126
	v_add_f32_e32 v215, v215, v218
	v_mul_f32_e32 v218, v121, v121
	v_mul_f32_e32 v219, v123, v123
	v_fmac_f32_e32 v218, v120, v120
	v_fmac_f32_e32 v219, v122, v122
	v_add_f32_e32 v218, v218, v219
	v_add_f32_e32 v215, v218, v215
	v_mul_f32_e32 v218, v117, v117
	v_mul_f32_e32 v219, v119, v119
	v_fmac_f32_e32 v218, v116, v116
	v_fmac_f32_e32 v219, v118, v118
	v_add_f32_e32 v218, v218, v219
	v_add_f32_e32 v215, v218, v215
	v_mul_f32_e32 v218, v113, v113
	v_mul_f32_e32 v219, v115, v115
	v_fmac_f32_e32 v218, v112, v112
	v_fmac_f32_e32 v219, v114, v114
	v_add_f32_e32 v218, v218, v219
	v_add_f32_e32 v215, v218, v215
	v_mov_b32_e32 v218, v215
	s_nop 1
	v_permlane16_swap_b32_e32 v215, v218
	v_cndmask_b32_e32 v208, v233, v208, vcc
	v_lshlrev_b32_e32 v208, 2, v208
	s_lshl_b32 s6, s46, 2
	v_readlane_b32 s81, v255, 1
	s_waitcnt lgkmcnt(0)
	v_add_f32_e32 v215, v215, v218
	v_mov_b32_e32 v218, v215
	s_nop 1
	v_permlane32_swap_b32_e32 v215, v218
	s_add_i32 s12, s6, 0
	s_and_saveexec_b64 s[6:7], s[4:5]
	s_cbranch_execz .LBB0_1271
	s_lshl_b32 s8, s31, 10
	s_add_i32 s8, s12, s8
	s_waitcnt lgkmcnt(0)
	v_add_f32_e32 v215, v215, v218
	v_lshl_add_u32 v218, v214, 4, s8
	ds_write_b32 v218, v215
.LBB0_1271:
	s_or_b64 exec, exec, s[6:7]
	v_mul_f32_e32 v215, v109, v109
	s_waitcnt lgkmcnt(0)
	v_mul_f32_e32 v218, v111, v111
	v_fmac_f32_e32 v215, v108, v108
	v_fmac_f32_e32 v218, v110, v110
	v_add_f32_e32 v215, v215, v218
	v_mul_f32_e32 v218, v105, v105
	v_mul_f32_e32 v219, v107, v107
	v_fmac_f32_e32 v218, v104, v104
	v_fmac_f32_e32 v219, v106, v106
	v_add_f32_e32 v218, v218, v219
	v_add_f32_e32 v215, v218, v215
	v_mul_f32_e32 v218, v101, v101
	v_mul_f32_e32 v219, v103, v103
	v_fmac_f32_e32 v218, v100, v100
	v_fmac_f32_e32 v219, v102, v102
	v_add_f32_e32 v218, v218, v219
	v_add_f32_e32 v215, v218, v215
	v_mul_f32_e32 v218, v97, v97
	v_mul_f32_e32 v219, v99, v99
	v_fmac_f32_e32 v218, v96, v96
	v_fmac_f32_e32 v219, v98, v98
	v_add_f32_e32 v218, v218, v219
	v_add_f32_e32 v215, v218, v215
	v_mov_b32_e32 v218, v215
	s_nop 1
	v_permlane16_swap_b32_e32 v215, v218
	s_waitcnt lgkmcnt(0)
	v_add_f32_e32 v215, v215, v218
	v_mov_b32_e32 v218, v215
	s_nop 1
	v_permlane32_swap_b32_e32 v215, v218
	s_and_saveexec_b64 s[6:7], s[4:5]
	v_readlane_b32 s52, v254, 56
	v_readlane_b32 s56, v255, 4
	v_readlane_b32 s53, v254, 57
	v_readlane_b32 s47, v254, 58
	v_readlane_b32 s57, v255, 5
	s_cbranch_execz .LBB0_1273
	s_lshl_b32 s8, s31, 10
	s_add_i32 s8, s12, s8
	s_waitcnt lgkmcnt(0)
	v_add_f32_e32 v215, v215, v218
	v_lshl_add_u32 v218, v214, 4, s8
	ds_write_b32 v218, v215 offset:256
.LBB0_1273:
	s_or_b64 exec, exec, s[6:7]
	v_mul_f32_e32 v215, v93, v93
	s_waitcnt lgkmcnt(0)
	v_mul_f32_e32 v218, v95, v95
	v_fmac_f32_e32 v215, v92, v92
	v_fmac_f32_e32 v218, v94, v94
	v_add_f32_e32 v215, v215, v218
	v_mul_f32_e32 v218, v89, v89
	v_mul_f32_e32 v219, v91, v91
	v_fmac_f32_e32 v218, v88, v88
	v_fmac_f32_e32 v219, v90, v90
	v_add_f32_e32 v218, v218, v219
	v_add_f32_e32 v215, v218, v215
	v_mul_f32_e32 v218, v85, v85
	v_mul_f32_e32 v219, v87, v87
	v_fmac_f32_e32 v218, v84, v84
	v_fmac_f32_e32 v219, v86, v86
	v_add_f32_e32 v218, v218, v219
	v_add_f32_e32 v215, v218, v215
	v_mul_f32_e32 v218, v81, v81
	v_mul_f32_e32 v219, v83, v83
	v_fmac_f32_e32 v218, v80, v80
	v_fmac_f32_e32 v219, v82, v82
	v_add_f32_e32 v218, v218, v219
	v_add_f32_e32 v215, v218, v215
	v_mov_b32_e32 v218, v215
	s_nop 1
	v_permlane16_swap_b32_e32 v215, v218
	s_waitcnt lgkmcnt(0)
	v_add_f32_e32 v215, v215, v218
	v_mov_b32_e32 v218, v215
	s_nop 1
	v_permlane32_swap_b32_e32 v215, v218
	s_and_saveexec_b64 s[6:7], s[4:5]
	s_cbranch_execz .LBB0_1275
	s_lshl_b32 s8, s31, 10
	s_add_i32 s8, s12, s8
	s_waitcnt lgkmcnt(0)
	v_add_f32_e32 v215, v215, v218
	v_lshl_add_u32 v218, v214, 4, s8
	ds_write_b32 v218, v215 offset:512
.LBB0_1275:
	s_or_b64 exec, exec, s[6:7]
	v_mul_f32_e32 v215, v77, v77
	s_waitcnt lgkmcnt(0)
	v_mul_f32_e32 v218, v79, v79
	v_fmac_f32_e32 v215, v76, v76
	v_fmac_f32_e32 v218, v78, v78
	v_add_f32_e32 v215, v215, v218
	v_mul_f32_e32 v218, v73, v73
	v_mul_f32_e32 v219, v75, v75
	v_fmac_f32_e32 v218, v72, v72
	v_fmac_f32_e32 v219, v74, v74
	v_add_f32_e32 v218, v218, v219
	v_add_f32_e32 v215, v218, v215
	v_mul_f32_e32 v218, v69, v69
	v_mul_f32_e32 v219, v71, v71
	v_fmac_f32_e32 v218, v68, v68
	v_fmac_f32_e32 v219, v70, v70
	v_add_f32_e32 v218, v218, v219
	v_add_f32_e32 v215, v218, v215
	v_mul_f32_e32 v218, v65, v65
	v_mul_f32_e32 v219, v67, v67
	v_fmac_f32_e32 v218, v64, v64
	v_fmac_f32_e32 v219, v66, v66
	v_add_f32_e32 v218, v218, v219
	v_add_f32_e32 v215, v218, v215
	v_mov_b32_e32 v218, v215
	s_nop 1
	v_permlane16_swap_b32_e32 v215, v218
	s_waitcnt lgkmcnt(0)
	v_add_f32_e32 v215, v215, v218
	v_mov_b32_e32 v218, v215
	s_nop 1
	v_permlane32_swap_b32_e32 v215, v218
	s_and_saveexec_b64 s[6:7], s[4:5]
	s_cbranch_execz .LBB0_1277
	s_lshl_b32 s8, s31, 10
	s_add_i32 s8, s12, s8
	s_waitcnt lgkmcnt(0)
	v_add_f32_e32 v215, v215, v218
	v_lshl_add_u32 v218, v214, 4, s8
	ds_write_b32 v218, v215 offset:768
.LBB0_1277:
	s_or_b64 exec, exec, s[6:7]
	v_mul_f32_e32 v215, v61, v61
	s_waitcnt lgkmcnt(0)
	v_mul_f32_e32 v218, v63, v63
	v_fmac_f32_e32 v215, v60, v60
	v_fmac_f32_e32 v218, v62, v62
	v_add_f32_e32 v215, v215, v218
	v_mul_f32_e32 v218, v57, v57
	v_mul_f32_e32 v219, v59, v59
	v_fmac_f32_e32 v218, v56, v56
	v_fmac_f32_e32 v219, v58, v58
	v_add_f32_e32 v218, v218, v219
	v_add_f32_e32 v215, v218, v215
	v_mul_f32_e32 v218, v53, v53
	v_mul_f32_e32 v219, v55, v55
	v_fmac_f32_e32 v218, v52, v52
	v_fmac_f32_e32 v219, v54, v54
	v_add_f32_e32 v218, v218, v219
	v_add_f32_e32 v215, v218, v215
	v_mul_f32_e32 v218, v49, v49
	v_mul_f32_e32 v219, v51, v51
	v_fmac_f32_e32 v218, v48, v48
	v_fmac_f32_e32 v219, v50, v50
	v_add_f32_e32 v218, v218, v219
	v_add_f32_e32 v215, v218, v215
	v_mov_b32_e32 v218, v215
	s_nop 1
	v_permlane16_swap_b32_e32 v215, v218
	s_waitcnt lgkmcnt(0)
	v_add_f32_e32 v215, v215, v218
	v_mov_b32_e32 v218, v215
	s_nop 1
	v_permlane32_swap_b32_e32 v215, v218
	s_and_saveexec_b64 s[6:7], s[4:5]
	s_cbranch_execz .LBB0_1279
	s_lshl_b32 s8, s31, 10
	s_add_i32 s8, s12, s8
	s_waitcnt lgkmcnt(0)
	v_add_f32_e32 v215, v215, v218
	v_lshl_add_u32 v218, v214, 4, s8
	ds_write_b32 v218, v215 offset:2048
.LBB0_1279:
	s_or_b64 exec, exec, s[6:7]
	v_mul_f32_e32 v215, v45, v45
	s_waitcnt lgkmcnt(0)
	v_mul_f32_e32 v218, v47, v47
	v_fmac_f32_e32 v215, v44, v44
	v_fmac_f32_e32 v218, v46, v46
	v_add_f32_e32 v215, v215, v218
	v_mul_f32_e32 v218, v41, v41
	v_mul_f32_e32 v219, v43, v43
	v_fmac_f32_e32 v218, v40, v40
	v_fmac_f32_e32 v219, v42, v42
	v_add_f32_e32 v218, v218, v219
	v_add_f32_e32 v215, v218, v215
	v_mul_f32_e32 v218, v37, v37
	v_mul_f32_e32 v219, v39, v39
	v_fmac_f32_e32 v218, v36, v36
	v_fmac_f32_e32 v219, v38, v38
	v_add_f32_e32 v218, v218, v219
	v_add_f32_e32 v215, v218, v215
	v_mul_f32_e32 v218, v33, v33
	v_mul_f32_e32 v219, v35, v35
	v_fmac_f32_e32 v218, v32, v32
	v_fmac_f32_e32 v219, v34, v34
	v_add_f32_e32 v218, v218, v219
	v_add_f32_e32 v215, v218, v215
	v_mov_b32_e32 v218, v215
	s_nop 1
	v_permlane16_swap_b32_e32 v215, v218
	s_waitcnt lgkmcnt(0)
	v_add_f32_e32 v215, v215, v218
	v_mov_b32_e32 v218, v215
	s_nop 1
	v_permlane32_swap_b32_e32 v215, v218
	s_and_saveexec_b64 s[6:7], s[4:5]
	s_cbranch_execz .LBB0_1281
	s_lshl_b32 s8, s31, 10
	s_add_i32 s8, s12, s8
	s_waitcnt lgkmcnt(0)
	v_add_f32_e32 v215, v215, v218
	v_lshl_add_u32 v218, v214, 4, s8
	ds_write_b32 v218, v215 offset:2304
.LBB0_1281:
	s_or_b64 exec, exec, s[6:7]
	v_mul_f32_e32 v215, v29, v29
	s_waitcnt lgkmcnt(0)
	v_mul_f32_e32 v218, v31, v31
	v_fmac_f32_e32 v215, v28, v28
	v_fmac_f32_e32 v218, v30, v30
	v_add_f32_e32 v215, v215, v218
	v_mul_f32_e32 v218, v25, v25
	v_mul_f32_e32 v219, v27, v27
	v_fmac_f32_e32 v218, v24, v24
	v_fmac_f32_e32 v219, v26, v26
	v_add_f32_e32 v218, v218, v219
	v_add_f32_e32 v215, v218, v215
	v_mul_f32_e32 v218, v21, v21
	v_mul_f32_e32 v219, v23, v23
	v_fmac_f32_e32 v218, v20, v20
	v_fmac_f32_e32 v219, v22, v22
	v_add_f32_e32 v218, v218, v219
	v_add_f32_e32 v215, v218, v215
	v_mul_f32_e32 v218, v17, v17
	v_mul_f32_e32 v219, v19, v19
	v_fmac_f32_e32 v218, v16, v16
	v_fmac_f32_e32 v219, v18, v18
	v_add_f32_e32 v218, v218, v219
	v_add_f32_e32 v215, v218, v215
	v_mov_b32_e32 v218, v215
	s_nop 1
	v_permlane16_swap_b32_e32 v215, v218
	s_waitcnt lgkmcnt(0)
	v_add_f32_e32 v215, v215, v218
	v_mov_b32_e32 v218, v215
	s_nop 1
	v_permlane32_swap_b32_e32 v215, v218
	s_and_saveexec_b64 s[6:7], s[4:5]
	s_cbranch_execz .LBB0_1283
	s_lshl_b32 s8, s31, 10
	s_add_i32 s8, s12, s8
	s_waitcnt lgkmcnt(0)
	v_add_f32_e32 v215, v215, v218
	v_lshl_add_u32 v218, v214, 4, s8
	ds_write_b32 v218, v215 offset:2560
.LBB0_1283:
	s_or_b64 exec, exec, s[6:7]
	v_mul_f32_e32 v215, v13, v13
	s_waitcnt lgkmcnt(0)
	v_mul_f32_e32 v218, v15, v15
	v_fmac_f32_e32 v215, v12, v12
	v_fmac_f32_e32 v218, v14, v14
	v_add_f32_e32 v215, v215, v218
	v_mul_f32_e32 v218, v9, v9
	v_mul_f32_e32 v219, v11, v11
	v_fmac_f32_e32 v218, v8, v8
	v_fmac_f32_e32 v219, v10, v10
	v_add_f32_e32 v218, v218, v219
	v_add_f32_e32 v215, v218, v215
	v_mul_f32_e32 v218, v5, v5
	v_mul_f32_e32 v219, v7, v7
	v_fmac_f32_e32 v218, v4, v4
	v_fmac_f32_e32 v219, v6, v6
	v_add_f32_e32 v218, v218, v219
	v_add_f32_e32 v215, v218, v215
	v_mul_f32_e32 v218, v1, v1
	v_mul_f32_e32 v219, v3, v3
	v_fmac_f32_e32 v218, v0, v0
	v_fmac_f32_e32 v219, v2, v2
	v_add_f32_e32 v218, v218, v219
	v_add_f32_e32 v215, v218, v215
	v_mov_b32_e32 v218, v215
	s_nop 1
	v_permlane16_swap_b32_e32 v215, v218
	s_waitcnt lgkmcnt(0)
	v_add_f32_e32 v215, v215, v218
	v_mov_b32_e32 v218, v215
	s_nop 1
	v_permlane32_swap_b32_e32 v215, v218
	s_and_saveexec_b64 s[6:7], s[4:5]
	s_cbranch_execz .LBB0_1285
	s_lshl_b32 s8, s31, 10
	s_add_i32 s8, s12, s8
	s_waitcnt lgkmcnt(0)
	v_add_f32_e32 v215, v215, v218
	v_lshl_add_u32 v214, v214, 4, s8
	ds_write_b32 v214, v215 offset:2816

.LBB0_1301:
	s_or_b64 exec, exec, s[22:23]
	s_waitcnt lgkmcnt(0)
	s_barrier
	v_lshl_add_u32 v249, v247, 2, 0
	s_waitcnt lgkmcnt(0)
	ds_read_b32 v218, v249 offset:4096
	v_add_u32_e32 v224, s13, v247
	v_ashrrev_i32_e32 v225, 31, v224
	v_lshlrev_b64 v[220:221], 11, v[224:225]
	v_readlane_b32 s30, v254, 62
	s_waitcnt lgkmcnt(0)
	v_pk_mul_f32 v[112:113], v[112:113], v[218:219] op_sel_hi:[1,0]
	v_lshl_add_u64 v[220:221], v[220:221], 0, v[212:213]
	s_waitcnt vmcnt(0)
	v_pk_fma_f32 v[112:113], v[128:129], v[112:113], v[192:193]
	v_lshlrev_b64 v[192:193], 13, v[224:225]
	v_pk_mul_f32 v[124:125], v[124:125], v[218:219] op_sel_hi:[1,0]
	v_pk_mul_f32 v[126:127], v[126:127], v[218:219] op_sel_hi:[1,0]
	v_readlane_b32 s31, v254, 63
	v_pk_mul_f32 v[120:121], v[120:121], v[218:219] op_sel_hi:[1,0]
	v_pk_mul_f32 v[122:123], v[122:123], v[218:219] op_sel_hi:[1,0]
	v_pk_mul_f32 v[116:117], v[116:117], v[218:219] op_sel_hi:[1,0]
	v_pk_mul_f32 v[118:119], v[118:119], v[218:219] op_sel_hi:[1,0]
	v_pk_mul_f32 v[114:115], v[114:115], v[218:219] op_sel_hi:[1,0]
	v_lshl_add_u64 v[192:193], v[216:217], 0, v[192:193]
	v_pk_fma_f32 v[126:127], v[142:143], v[126:127], v[206:207]
	v_pk_fma_f32 v[124:125], v[140:141], v[124:125], v[204:205]
	v_lshl_add_u64 v[204:205], v[220:221], 2, s[30:31]
	v_pk_fma_f32 v[122:123], v[138:139], v[122:123], v[202:203]
	v_pk_fma_f32 v[120:121], v[136:137], v[120:121], v[200:201]
	v_pk_fma_f32 v[118:119], v[134:135], v[118:119], v[198:199]
	v_pk_fma_f32 v[116:117], v[132:133], v[116:117], v[196:197]
	v_pk_fma_f32 v[114:115], v[130:131], v[114:115], v[194:195]
	v_add_co_u32_e32 v192, vcc, 0x100000, v192
	global_store_dwordx4 v[204:205], v[124:127], off
	global_store_dwordx4 v[204:205], v[120:123], off offset:64
	global_store_dwordx4 v[204:205], v[116:119], off offset:512
	global_store_dwordx4 v[204:205], v[112:115], off offset:576
	v_addc_co_u32_e32 v193, vcc, 0, v193, vcc
	global_load_dwordx4 v[204:207], v[192:193], off
	global_load_dwordx4 v[200:203], v[192:193], off offset:64
	global_load_dwordx4 v[196:199], v[192:193], off offset:512
	s_nop 0
	global_load_dwordx4 v[192:195], v[192:193], off offset:576
	v_mul_f32_e32 v218, v125, v125
	v_mul_f32_e32 v219, v127, v127
	v_fmac_f32_e32 v218, v124, v124
	v_fmac_f32_e32 v219, v126, v126
	v_add_f32_e32 v218, v218, v219
	v_mul_f32_e32 v219, v121, v121
	v_mul_f32_e32 v220, v123, v123
	v_fmac_f32_e32 v219, v120, v120
	v_fmac_f32_e32 v220, v122, v122
	v_add_f32_e32 v219, v219, v220
	v_add_f32_e32 v218, v218, v219
	v_mul_f32_e32 v219, v117, v117
	v_mul_f32_e32 v220, v119, v119
	v_fmac_f32_e32 v219, v116, v116
	v_fmac_f32_e32 v220, v118, v118
	v_add_f32_e32 v219, v219, v220
	v_add_f32_e32 v218, v219, v218
	v_mul_f32_e32 v219, v113, v113
	v_mul_f32_e32 v220, v115, v115
	v_fmac_f32_e32 v219, v112, v112
	v_fmac_f32_e32 v220, v114, v114
	v_add_f32_e32 v219, v219, v220
	v_add_f32_e32 v218, v219, v218
	v_mov_b32_e32 v219, v218
	s_nop 1
	v_permlane16_swap_b32_e32 v218, v219
	s_waitcnt lgkmcnt(0)
	v_add_f32_e32 v218, v218, v219
	v_mov_b32_e32 v219, v218
	s_nop 1
	v_permlane32_swap_b32_e32 v218, v219
	s_and_saveexec_b64 s[14:15], s[4:5]
	s_cbranch_execz .LBB0_1303
	v_lshl_add_u32 v220, v247, 4, s12
	s_waitcnt lgkmcnt(0)
	v_add_f32_e32 v218, v218, v219
	ds_write_b32 v220, v218
.LBB0_1303:
	s_or_b64 exec, exec, s[14:15]
	ds_read_b32 v220, v249 offset:4160
	v_or_b32_e32 v218, 16, v247
	v_add_u32_e32 v222, s13, v218
	v_ashrrev_i32_e32 v223, 31, v222
	v_lshlrev_b64 v[250:251], 11, v[222:223]
	s_waitcnt lgkmcnt(0)
	v_pk_mul_f32 v[96:97], v[96:97], v[220:221] op_sel_hi:[1,0]
	v_lshl_add_u64 v[250:251], v[250:251], 0, v[212:213]
	v_pk_fma_f32 v[96:97], v[128:129], v[96:97], v[176:177]
	v_lshlrev_b64 v[176:177], 13, v[222:223]
	v_pk_mul_f32 v[110:111], v[110:111], v[220:221] op_sel_hi:[1,0]
	v_pk_mul_f32 v[108:109], v[108:109], v[220:221] op_sel_hi:[1,0]
	v_pk_mul_f32 v[106:107], v[106:107], v[220:221] op_sel_hi:[1,0]
	v_pk_mul_f32 v[104:105], v[104:105], v[220:221] op_sel_hi:[1,0]
	v_pk_mul_f32 v[102:103], v[102:103], v[220:221] op_sel_hi:[1,0]
	v_pk_mul_f32 v[100:101], v[100:101], v[220:221] op_sel_hi:[1,0]
	v_pk_mul_f32 v[98:99], v[98:99], v[220:221] op_sel_hi:[1,0]
	v_lshl_add_u64 v[176:177], v[216:217], 0, v[176:177]
	v_pk_fma_f32 v[110:111], v[142:143], v[110:111], v[190:191]
	v_pk_fma_f32 v[108:109], v[140:141], v[108:109], v[188:189]
	v_lshl_add_u64 v[188:189], v[250:251], 2, s[30:31]
	v_pk_fma_f32 v[106:107], v[138:139], v[106:107], v[186:187]
	v_pk_fma_f32 v[104:105], v[136:137], v[104:105], v[184:185]
	v_pk_fma_f32 v[102:103], v[134:135], v[102:103], v[182:183]
	v_pk_fma_f32 v[100:101], v[132:133], v[100:101], v[180:181]
	v_pk_fma_f32 v[98:99], v[130:131], v[98:99], v[178:179]
	v_add_co_u32_e32 v176, vcc, 0x100000, v176
	global_store_dwordx4 v[188:189], v[108:111], off
	global_store_dwordx4 v[188:189], v[104:107], off offset:64
	global_store_dwordx4 v[188:189], v[100:103], off offset:512
	global_store_dwordx4 v[188:189], v[96:99], off offset:576
	v_addc_co_u32_e32 v177, vcc, 0, v177, vcc
	global_load_dwordx4 v[188:191], v[176:177], off
	global_load_dwordx4 v[184:187], v[176:177], off offset:64
	global_load_dwordx4 v[180:183], v[176:177], off offset:512
	s_nop 0
	global_load_dwordx4 v[176:179], v[176:177], off offset:576
	v_mul_f32_e32 v219, v109, v109
	v_mul_f32_e32 v220, v111, v111
	v_fmac_f32_e32 v219, v108, v108
	v_fmac_f32_e32 v220, v110, v110
	v_add_f32_e32 v219, v219, v220
	v_mul_f32_e32 v220, v105, v105
	v_mul_f32_e32 v221, v107, v107
	v_fmac_f32_e32 v220, v104, v104
	v_fmac_f32_e32 v221, v106, v106
	v_add_f32_e32 v220, v220, v221
	v_add_f32_e32 v219, v219, v220
	v_mul_f32_e32 v220, v101, v101
	v_mul_f32_e32 v221, v103, v103
	v_fmac_f32_e32 v220, v100, v100
	v_fmac_f32_e32 v221, v102, v102
	v_add_f32_e32 v220, v220, v221
	v_add_f32_e32 v219, v220, v219
	v_mul_f32_e32 v220, v97, v97
	v_mul_f32_e32 v221, v99, v99
	v_fmac_f32_e32 v220, v96, v96
	v_fmac_f32_e32 v221, v98, v98
	v_add_f32_e32 v220, v220, v221
	v_add_f32_e32 v219, v220, v219
	v_mov_b32_e32 v220, v219
	s_nop 1
	v_permlane16_swap_b32_e32 v219, v220
	s_waitcnt lgkmcnt(0)
	v_add_f32_e32 v219, v219, v220
	v_mov_b32_e32 v220, v219
	s_nop 1
	v_permlane32_swap_b32_e32 v219, v220
	s_and_saveexec_b64 s[14:15], s[4:5]
	s_cbranch_execz .LBB0_1305
	v_lshl_add_u32 v218, v218, 4, s12
	s_waitcnt lgkmcnt(0)
	v_add_f32_e32 v219, v219, v220
	ds_write_b32 v218, v219
.LBB0_1305:
	s_or_b64 exec, exec, s[14:15]
	ds_read_b32 v250, v249 offset:4224
	v_or_b32_e32 v218, 32, v247
	s_waitcnt lgkmcnt(1)
	v_add_u32_e32 v220, s13, v218
	v_ashrrev_i32_e32 v221, 31, v220
	v_lshlrev_b64 v[252:253], 11, v[220:221]
	s_waitcnt lgkmcnt(0)
	v_pk_mul_f32 v[80:81], v[80:81], v[250:251] op_sel_hi:[1,0]
	v_lshl_add_u64 v[252:253], v[252:253], 0, v[212:213]
	v_pk_fma_f32 v[80:81], v[128:129], v[80:81], v[160:161]
	v_lshlrev_b64 v[160:161], 13, v[220:221]
	v_pk_mul_f32 v[94:95], v[94:95], v[250:251] op_sel_hi:[1,0]
	v_pk_mul_f32 v[92:93], v[92:93], v[250:251] op_sel_hi:[1,0]
	v_pk_mul_f32 v[90:91], v[90:91], v[250:251] op_sel_hi:[1,0]
	v_pk_mul_f32 v[88:89], v[88:89], v[250:251] op_sel_hi:[1,0]
	v_pk_mul_f32 v[86:87], v[86:87], v[250:251] op_sel_hi:[1,0]
	v_pk_mul_f32 v[84:85], v[84:85], v[250:251] op_sel_hi:[1,0]
	v_pk_mul_f32 v[82:83], v[82:83], v[250:251] op_sel_hi:[1,0]
	v_lshl_add_u64 v[160:161], v[216:217], 0, v[160:161]
	v_pk_fma_f32 v[94:95], v[142:143], v[94:95], v[174:175]
	v_pk_fma_f32 v[92:93], v[140:141], v[92:93], v[172:173]
	v_lshl_add_u64 v[172:173], v[252:253], 2, s[30:31]
	v_pk_fma_f32 v[90:91], v[138:139], v[90:91], v[170:171]
	v_pk_fma_f32 v[88:89], v[136:137], v[88:89], v[168:169]
	v_pk_fma_f32 v[86:87], v[134:135], v[86:87], v[166:167]
	v_pk_fma_f32 v[84:85], v[132:133], v[84:85], v[164:165]
	v_pk_fma_f32 v[82:83], v[130:131], v[82:83], v[162:163]
	v_add_co_u32_e32 v160, vcc, 0x100000, v160
	global_store_dwordx4 v[172:173], v[92:95], off
	global_store_dwordx4 v[172:173], v[88:91], off offset:64
	global_store_dwordx4 v[172:173], v[84:87], off offset:512
	global_store_dwordx4 v[172:173], v[80:83], off offset:576
	v_addc_co_u32_e32 v161, vcc, 0, v161, vcc
	global_load_dwordx4 v[172:175], v[160:161], off
	global_load_dwordx4 v[168:171], v[160:161], off offset:64
	global_load_dwordx4 v[164:167], v[160:161], off offset:512
	s_nop 0
	global_load_dwordx4 v[160:163], v[160:161], off offset:576
	v_mul_f32_e32 v219, v93, v93
	v_mul_f32_e32 v228, v95, v95
	v_fmac_f32_e32 v219, v92, v92
	v_fmac_f32_e32 v228, v94, v94
	v_add_f32_e32 v219, v219, v228
	v_mul_f32_e32 v228, v89, v89
	v_mul_f32_e32 v229, v91, v91
	v_fmac_f32_e32 v228, v88, v88
	v_fmac_f32_e32 v229, v90, v90
	v_add_f32_e32 v228, v228, v229
	v_add_f32_e32 v219, v219, v228
	v_mul_f32_e32 v228, v85, v85
	v_mul_f32_e32 v229, v87, v87
	v_fmac_f32_e32 v228, v84, v84
	v_fmac_f32_e32 v229, v86, v86
	v_add_f32_e32 v228, v228, v229
	v_add_f32_e32 v219, v228, v219
	v_mul_f32_e32 v228, v81, v81
	v_mul_f32_e32 v229, v83, v83
	v_fmac_f32_e32 v228, v80, v80
	v_fmac_f32_e32 v229, v82, v82
	v_add_f32_e32 v228, v228, v229
	v_add_f32_e32 v219, v228, v219
	v_mov_b32_e32 v228, v219
	s_nop 1
	v_permlane16_swap_b32_e32 v219, v228
	s_waitcnt lgkmcnt(0)
	v_add_f32_e32 v219, v219, v228
	v_mov_b32_e32 v250, v219
	s_nop 1
	v_permlane32_swap_b32_e32 v219, v250
	s_and_saveexec_b64 s[14:15], s[4:5]
	s_cbranch_execz .LBB0_1307
	v_lshl_add_u32 v218, v218, 4, s12
	s_waitcnt lgkmcnt(0)
	v_add_f32_e32 v219, v219, v250
	ds_write_b32 v218, v219
.LBB0_1307:
	s_or_b64 exec, exec, s[14:15]
	ds_read_b32 v252, v249 offset:4288
	s_waitcnt lgkmcnt(1)
	v_or_b32_e32 v250, 48, v247
	v_add_u32_e32 v218, s13, v250
	v_ashrrev_i32_e32 v219, 31, v218
	v_lshlrev_b64 v[228:229], 11, v[218:219]
	s_waitcnt lgkmcnt(0)
	v_pk_mul_f32 v[64:65], v[64:65], v[252:253] op_sel_hi:[1,0]
	v_lshl_add_u64 v[228:229], v[228:229], 0, v[212:213]
	v_pk_fma_f32 v[64:65], v[128:129], v[64:65], v[144:145]
	v_lshlrev_b64 v[144:145], 13, v[218:219]
	v_pk_mul_f32 v[78:79], v[78:79], v[252:253] op_sel_hi:[1,0]
	v_pk_mul_f32 v[76:77], v[76:77], v[252:253] op_sel_hi:[1,0]
	v_pk_mul_f32 v[74:75], v[74:75], v[252:253] op_sel_hi:[1,0]
	v_pk_mul_f32 v[72:73], v[72:73], v[252:253] op_sel_hi:[1,0]
	v_pk_mul_f32 v[70:71], v[70:71], v[252:253] op_sel_hi:[1,0]
	v_pk_mul_f32 v[68:69], v[68:69], v[252:253] op_sel_hi:[1,0]
	v_pk_mul_f32 v[66:67], v[66:67], v[252:253] op_sel_hi:[1,0]
	v_lshl_add_u64 v[144:145], v[216:217], 0, v[144:145]
	v_pk_fma_f32 v[78:79], v[142:143], v[78:79], v[158:159]
	v_pk_fma_f32 v[76:77], v[140:141], v[76:77], v[156:157]
	v_lshl_add_u64 v[156:157], v[228:229], 2, s[30:31]
	v_pk_fma_f32 v[74:75], v[138:139], v[74:75], v[154:155]
	v_pk_fma_f32 v[72:73], v[136:137], v[72:73], v[152:153]
	v_pk_fma_f32 v[70:71], v[134:135], v[70:71], v[150:151]
	v_pk_fma_f32 v[68:69], v[132:133], v[68:69], v[148:149]
	v_pk_fma_f32 v[66:67], v[130:131], v[66:67], v[146:147]
	v_add_co_u32_e32 v144, vcc, 0x100000, v144
	global_store_dwordx4 v[156:157], v[76:79], off
	global_store_dwordx4 v[156:157], v[72:75], off offset:64
	global_store_dwordx4 v[156:157], v[68:71], off offset:512
	global_store_dwordx4 v[156:157], v[64:67], off offset:576
	v_addc_co_u32_e32 v145, vcc, 0, v145, vcc
	global_load_dwordx4 v[156:159], v[144:145], off
	global_load_dwordx4 v[152:155], v[144:145], off offset:64
	global_load_dwordx4 v[148:151], v[144:145], off offset:512
	s_nop 0
	global_load_dwordx4 v[144:147], v[144:145], off offset:576
	v_mul_f32_e32 v216, v77, v77
	v_mul_f32_e32 v217, v79, v79
	v_fmac_f32_e32 v216, v76, v76
	v_fmac_f32_e32 v217, v78, v78
	v_add_f32_e32 v216, v216, v217
	v_mul_f32_e32 v217, v73, v73
	v_mul_f32_e32 v228, v75, v75
	v_fmac_f32_e32 v217, v72, v72
	v_fmac_f32_e32 v228, v74, v74
	v_add_f32_e32 v217, v217, v228
	v_add_f32_e32 v216, v216, v217
	v_mul_f32_e32 v217, v69, v69
	v_mul_f32_e32 v228, v71, v71
	v_fmac_f32_e32 v217, v68, v68
	v_fmac_f32_e32 v228, v70, v70
	v_add_f32_e32 v217, v217, v228
	v_add_f32_e32 v216, v217, v216
	v_mul_f32_e32 v217, v65, v65
	v_mul_f32_e32 v228, v67, v67
	v_fmac_f32_e32 v217, v64, v64
	v_fmac_f32_e32 v228, v66, v66
	v_add_f32_e32 v217, v217, v228
	v_add_f32_e32 v216, v217, v216
	v_mov_b32_e32 v217, v216
	s_nop 1
	v_permlane16_swap_b32_e32 v216, v217
	s_waitcnt lgkmcnt(0)
	v_add_f32_e32 v216, v216, v217
	v_mov_b32_e32 v217, v216
	s_nop 1
	v_permlane32_swap_b32_e32 v216, v217
	s_and_saveexec_b64 s[14:15], s[4:5]
	s_cbranch_execz .LBB0_1309
	v_lshl_add_u32 v228, v250, 4, s12
	s_waitcnt lgkmcnt(0)
	v_add_f32_e32 v216, v216, v217
	ds_write_b32 v228, v216
.LBB0_1309:
	s_or_b64 exec, exec, s[14:15]
	ds_read_b32 v228, v249 offset:4608
	v_add_u32_e32 v250, 0x80, v247
	v_add_u32_e32 v216, s13, v250
	s_waitcnt lgkmcnt(1)
	v_ashrrev_i32_e32 v217, 31, v216
	s_waitcnt lgkmcnt(0)
	v_pk_mul_f32 v[62:63], v[62:63], v[228:229] op_sel_hi:[1,0]
	v_pk_mul_f32 v[60:61], v[60:61], v[228:229] op_sel_hi:[1,0]
	s_waitcnt vmcnt(27)
	v_pk_fma_f32 v[62:63], v[142:143], v[62:63], v[206:207]
	v_pk_fma_f32 v[60:61], v[140:141], v[60:61], v[204:205]
	v_pk_mul_f32 v[48:49], v[48:49], v[228:229] op_sel_hi:[1,0]
	v_pk_mul_f32 v[58:59], v[58:59], v[228:229] op_sel_hi:[1,0]
	v_pk_mul_f32 v[56:57], v[56:57], v[228:229] op_sel_hi:[1,0]
	s_waitcnt vmcnt(24)
	v_pk_fma_f32 v[48:49], v[128:129], v[48:49], v[192:193]
	v_mul_f32_e32 v192, v61, v61
	v_mul_f32_e32 v193, v63, v63
	v_pk_fma_f32 v[58:59], v[138:139], v[58:59], v[202:203]
	v_pk_fma_f32 v[56:57], v[136:137], v[56:57], v[200:201]
	v_pk_mul_f32 v[50:51], v[50:51], v[228:229] op_sel_hi:[1,0]
	v_fmac_f32_e32 v192, v60, v60
	v_fmac_f32_e32 v193, v62, v62
	v_pk_fma_f32 v[50:51], v[130:131], v[50:51], v[194:195]
	v_add_f32_e32 v192, v192, v193
	v_mul_f32_e32 v193, v57, v57
	v_mul_f32_e32 v194, v59, v59
	v_pk_mul_f32 v[54:55], v[54:55], v[228:229] op_sel_hi:[1,0]
	v_pk_mul_f32 v[52:53], v[52:53], v[228:229] op_sel_hi:[1,0]
	v_fmac_f32_e32 v193, v56, v56
	v_fmac_f32_e32 v194, v58, v58
	v_pk_fma_f32 v[54:55], v[134:135], v[54:55], v[198:199]
	v_pk_fma_f32 v[52:53], v[132:133], v[52:53], v[196:197]
	v_add_f32_e32 v193, v193, v194
	v_add_f32_e32 v192, v192, v193
	v_mul_f32_e32 v193, v53, v53
	v_mul_f32_e32 v194, v55, v55
	v_fmac_f32_e32 v193, v52, v52
	v_fmac_f32_e32 v194, v54, v54
	v_add_f32_e32 v193, v193, v194
	v_add_f32_e32 v192, v193, v192
	v_mul_f32_e32 v193, v49, v49
	v_mul_f32_e32 v194, v51, v51
	v_fmac_f32_e32 v193, v48, v48
	v_fmac_f32_e32 v194, v50, v50
	v_add_f32_e32 v193, v193, v194
	v_add_f32_e32 v196, v193, v192
	v_mov_b32_e32 v197, v196
	s_nop 1
	v_permlane16_swap_b32_e32 v196, v197
	v_lshlrev_b64 v[192:193], 13, v[216:217]
	v_lshl_add_u64 v[192:193], s[30:31], 0, v[192:193]
	v_lshl_add_u64 v[194:195], v[212:213], 2, v[192:193]
	global_store_dwordx4 v[194:195], v[60:63], off
	global_store_dwordx4 v[194:195], v[56:59], off offset:64
	global_store_dwordx4 v[194:195], v[52:55], off offset:512
	global_store_dwordx4 v[194:195], v[48:51], off offset:576
	s_waitcnt lgkmcnt(0)
	v_add_f32_e32 v192, v196, v197
	v_mov_b32_e32 v193, v192
	s_nop 1
	v_permlane32_swap_b32_e32 v192, v193
	s_and_saveexec_b64 s[14:15], s[4:5]
	s_cbranch_execz .LBB0_1311
	v_lshl_add_u32 v194, v250, 4, s12
	s_waitcnt lgkmcnt(0)
	v_add_f32_e32 v192, v192, v193
	ds_write_b32 v194, v192
.LBB0_1311:
	s_or_b64 exec, exec, s[14:15]
	ds_read_b32 v196, v249 offset:4672
	v_add_u32_e32 v194, 0x90, v247
	v_add_u32_e32 v192, s13, v194
	s_waitcnt lgkmcnt(1)
	v_ashrrev_i32_e32 v193, 31, v192
	s_waitcnt lgkmcnt(0)
	v_pk_mul_f32 v[46:47], v[46:47], v[196:197] op_sel_hi:[1,0]
	v_pk_mul_f32 v[44:45], v[44:45], v[196:197] op_sel_hi:[1,0]
	s_waitcnt vmcnt(23)
	v_pk_fma_f32 v[46:47], v[142:143], v[46:47], v[190:191]
	v_pk_fma_f32 v[44:45], v[140:141], v[44:45], v[188:189]
	v_pk_mul_f32 v[32:33], v[32:33], v[196:197] op_sel_hi:[1,0]
	v_pk_mul_f32 v[42:43], v[42:43], v[196:197] op_sel_hi:[1,0]
	v_pk_mul_f32 v[40:41], v[40:41], v[196:197] op_sel_hi:[1,0]
	s_waitcnt vmcnt(20)
	v_pk_fma_f32 v[32:33], v[128:129], v[32:33], v[176:177]
	v_mul_f32_e32 v176, v45, v45
	v_mul_f32_e32 v177, v47, v47
	v_pk_fma_f32 v[42:43], v[138:139], v[42:43], v[186:187]
	v_pk_fma_f32 v[40:41], v[136:137], v[40:41], v[184:185]
	v_pk_mul_f32 v[34:35], v[34:35], v[196:197] op_sel_hi:[1,0]
	v_fmac_f32_e32 v176, v44, v44
	v_fmac_f32_e32 v177, v46, v46
	v_pk_fma_f32 v[34:35], v[130:131], v[34:35], v[178:179]
	v_add_f32_e32 v176, v176, v177
	v_mul_f32_e32 v177, v41, v41
	v_mul_f32_e32 v178, v43, v43
	v_pk_mul_f32 v[38:39], v[38:39], v[196:197] op_sel_hi:[1,0]
	v_pk_mul_f32 v[36:37], v[36:37], v[196:197] op_sel_hi:[1,0]
	v_fmac_f32_e32 v177, v40, v40
	v_fmac_f32_e32 v178, v42, v42
	v_pk_fma_f32 v[38:39], v[134:135], v[38:39], v[182:183]
	v_pk_fma_f32 v[36:37], v[132:133], v[36:37], v[180:181]
	v_add_f32_e32 v177, v177, v178
	v_add_f32_e32 v176, v176, v177
	v_mul_f32_e32 v177, v37, v37
	v_mul_f32_e32 v178, v39, v39
	v_fmac_f32_e32 v177, v36, v36
	v_fmac_f32_e32 v178, v38, v38
	v_add_f32_e32 v177, v177, v178
	v_add_f32_e32 v176, v177, v176
	v_mul_f32_e32 v177, v33, v33
	v_mul_f32_e32 v178, v35, v35
	v_fmac_f32_e32 v177, v32, v32
	v_fmac_f32_e32 v178, v34, v34
	v_add_f32_e32 v177, v177, v178
	v_add_f32_e32 v180, v177, v176
	v_mov_b32_e32 v181, v180
	s_nop 1
	v_permlane16_swap_b32_e32 v180, v181
	v_lshlrev_b64 v[176:177], 13, v[192:193]
	v_lshl_add_u64 v[176:177], s[30:31], 0, v[176:177]
	v_lshl_add_u64 v[178:179], v[212:213], 2, v[176:177]
	global_store_dwordx4 v[178:179], v[44:47], off
	global_store_dwordx4 v[178:179], v[40:43], off offset:64
	global_store_dwordx4 v[178:179], v[36:39], off offset:512
	global_store_dwordx4 v[178:179], v[32:35], off offset:576
	s_waitcnt lgkmcnt(0)
	v_add_f32_e32 v176, v180, v181
	v_mov_b32_e32 v177, v176
	s_nop 1
	v_permlane32_swap_b32_e32 v176, v177
	s_and_saveexec_b64 s[14:15], s[4:5]
	s_cbranch_execz .LBB0_1313
	v_lshl_add_u32 v178, v194, 4, s12
	s_waitcnt lgkmcnt(0)
	v_add_f32_e32 v176, v176, v177
	ds_write_b32 v178, v176
.LBB0_1313:
	s_or_b64 exec, exec, s[14:15]
	ds_read_b32 v180, v249 offset:4736
	v_add_u32_e32 v178, 0xa0, v247
	v_add_u32_e32 v176, s13, v178
	s_waitcnt lgkmcnt(1)
	v_ashrrev_i32_e32 v177, 31, v176
	s_waitcnt lgkmcnt(0)
	v_pk_mul_f32 v[30:31], v[30:31], v[180:181] op_sel_hi:[1,0]
	v_pk_mul_f32 v[28:29], v[28:29], v[180:181] op_sel_hi:[1,0]
	s_waitcnt vmcnt(19)
	v_pk_fma_f32 v[30:31], v[142:143], v[30:31], v[174:175]
	v_pk_fma_f32 v[28:29], v[140:141], v[28:29], v[172:173]
	v_pk_mul_f32 v[16:17], v[16:17], v[180:181] op_sel_hi:[1,0]
	v_pk_mul_f32 v[26:27], v[26:27], v[180:181] op_sel_hi:[1,0]
	v_pk_mul_f32 v[24:25], v[24:25], v[180:181] op_sel_hi:[1,0]
	s_waitcnt vmcnt(16)
	v_pk_fma_f32 v[16:17], v[128:129], v[16:17], v[160:161]
	v_mul_f32_e32 v160, v29, v29
	v_mul_f32_e32 v161, v31, v31
	v_pk_fma_f32 v[26:27], v[138:139], v[26:27], v[170:171]
	v_pk_fma_f32 v[24:25], v[136:137], v[24:25], v[168:169]
	v_pk_mul_f32 v[18:19], v[18:19], v[180:181] op_sel_hi:[1,0]
	v_fmac_f32_e32 v160, v28, v28
	v_fmac_f32_e32 v161, v30, v30
	v_pk_fma_f32 v[18:19], v[130:131], v[18:19], v[162:163]
	v_add_f32_e32 v160, v160, v161
	v_mul_f32_e32 v161, v25, v25
	v_mul_f32_e32 v162, v27, v27
	v_pk_mul_f32 v[22:23], v[22:23], v[180:181] op_sel_hi:[1,0]
	v_pk_mul_f32 v[20:21], v[20:21], v[180:181] op_sel_hi:[1,0]
	v_fmac_f32_e32 v161, v24, v24
	v_fmac_f32_e32 v162, v26, v26
	v_pk_fma_f32 v[22:23], v[134:135], v[22:23], v[166:167]
	v_pk_fma_f32 v[20:21], v[132:133], v[20:21], v[164:165]
	v_add_f32_e32 v161, v161, v162
	v_add_f32_e32 v160, v160, v161
	v_mul_f32_e32 v161, v21, v21
	v_mul_f32_e32 v162, v23, v23
	v_fmac_f32_e32 v161, v20, v20
	v_fmac_f32_e32 v162, v22, v22
	v_add_f32_e32 v161, v161, v162
	v_add_f32_e32 v160, v161, v160
	v_mul_f32_e32 v161, v17, v17
	v_mul_f32_e32 v162, v19, v19
	v_fmac_f32_e32 v161, v16, v16
	v_fmac_f32_e32 v162, v18, v18
	v_add_f32_e32 v161, v161, v162
	v_add_f32_e32 v164, v161, v160
	v_mov_b32_e32 v165, v164
	s_nop 1
	v_permlane16_swap_b32_e32 v164, v165
	v_lshlrev_b64 v[160:161], 13, v[176:177]
	v_lshl_add_u64 v[160:161], s[30:31], 0, v[160:161]
	v_lshl_add_u64 v[162:163], v[212:213], 2, v[160:161]
	global_store_dwordx4 v[162:163], v[28:31], off
	global_store_dwordx4 v[162:163], v[24:27], off offset:64
	global_store_dwordx4 v[162:163], v[20:23], off offset:512
	global_store_dwordx4 v[162:163], v[16:19], off offset:576
	s_waitcnt lgkmcnt(0)
	v_add_f32_e32 v160, v164, v165
	v_mov_b32_e32 v161, v160
	s_nop 1
	v_permlane32_swap_b32_e32 v160, v161
	s_and_saveexec_b64 s[14:15], s[4:5]
	s_cbranch_execz .LBB0_1315
	v_lshl_add_u32 v162, v178, 4, s12
	s_waitcnt lgkmcnt(0)
	v_add_f32_e32 v160, v160, v161
	ds_write_b32 v162, v160
.LBB0_1315:
	s_or_b64 exec, exec, s[14:15]
	ds_read_b32 v164, v249 offset:4800
	v_add_u32_e32 v162, 0xb0, v247
	v_add_u32_e32 v160, s13, v162
	s_waitcnt lgkmcnt(1)
	v_ashrrev_i32_e32 v161, 31, v160
	s_waitcnt lgkmcnt(0)
	v_pk_mul_f32 v[14:15], v[14:15], v[164:165] op_sel_hi:[1,0]
	v_pk_mul_f32 v[12:13], v[12:13], v[164:165] op_sel_hi:[1,0]
	s_waitcnt vmcnt(15)
	v_pk_fma_f32 v[14:15], v[142:143], v[14:15], v[158:159]
	v_pk_fma_f32 v[12:13], v[140:141], v[12:13], v[156:157]
	v_pk_mul_f32 v[0:1], v[0:1], v[164:165] op_sel_hi:[1,0]
	v_pk_mul_f32 v[10:11], v[10:11], v[164:165] op_sel_hi:[1,0]
	v_pk_mul_f32 v[8:9], v[8:9], v[164:165] op_sel_hi:[1,0]
	s_waitcnt vmcnt(12)
	v_pk_fma_f32 v[0:1], v[128:129], v[0:1], v[144:145]
	v_mul_f32_e32 v128, v13, v13
	v_mul_f32_e32 v129, v15, v15
	v_pk_fma_f32 v[10:11], v[138:139], v[10:11], v[154:155]
	v_pk_fma_f32 v[8:9], v[136:137], v[8:9], v[152:153]
	v_pk_mul_f32 v[2:3], v[2:3], v[164:165] op_sel_hi:[1,0]
	v_fmac_f32_e32 v128, v12, v12
	v_fmac_f32_e32 v129, v14, v14
	v_pk_fma_f32 v[2:3], v[130:131], v[2:3], v[146:147]
	v_add_f32_e32 v128, v128, v129
	v_mul_f32_e32 v129, v9, v9
	v_mul_f32_e32 v130, v11, v11
	v_pk_mul_f32 v[6:7], v[6:7], v[164:165] op_sel_hi:[1,0]
	v_pk_mul_f32 v[4:5], v[4:5], v[164:165] op_sel_hi:[1,0]
	v_fmac_f32_e32 v129, v8, v8
	v_fmac_f32_e32 v130, v10, v10
	v_pk_fma_f32 v[6:7], v[134:135], v[6:7], v[150:151]
	v_pk_fma_f32 v[4:5], v[132:133], v[4:5], v[148:149]
	v_add_f32_e32 v129, v129, v130
	v_add_f32_e32 v128, v128, v129
	v_mul_f32_e32 v129, v5, v5
	v_mul_f32_e32 v130, v7, v7
	v_fmac_f32_e32 v129, v4, v4
	v_fmac_f32_e32 v130, v6, v6
	v_add_f32_e32 v129, v129, v130
	v_add_f32_e32 v128, v129, v128
	v_mul_f32_e32 v129, v1, v1
	v_mul_f32_e32 v130, v3, v3
	v_fmac_f32_e32 v129, v0, v0
	v_fmac_f32_e32 v130, v2, v2
	v_add_f32_e32 v129, v129, v130
	v_add_f32_e32 v132, v129, v128
	v_mov_b32_e32 v133, v132
	s_nop 1
	v_permlane16_swap_b32_e32 v132, v133
	v_lshlrev_b64 v[128:129], 13, v[160:161]
	v_lshl_add_u64 v[128:129], s[30:31], 0, v[128:129]
	v_lshl_add_u64 v[130:131], v[212:213], 2, v[128:129]
	global_store_dwordx4 v[130:131], v[12:15], off
	global_store_dwordx4 v[130:131], v[8:11], off offset:64
	global_store_dwordx4 v[130:131], v[4:7], off offset:512
	global_store_dwordx4 v[130:131], v[0:3], off offset:576
	s_waitcnt lgkmcnt(0)
	v_add_f32_e32 v128, v132, v133
	v_mov_b32_e32 v129, v128
	s_nop 1
	v_permlane32_swap_b32_e32 v128, v129
	s_and_saveexec_b64 s[14:15], s[4:5]
	s_cbranch_execz .LBB0_1317
	v_lshl_add_u32 v130, v162, 4, s12
	s_waitcnt lgkmcnt(0)
	v_add_f32_e32 v128, v128, v129
	ds_write_b32 v130, v128
